# scan: per-element 2-byte LDS reads issued together after the first MFMA group into the other direction's (dead) weight registers
# speedup vs baseline: 1.0009x; 1.0009x over previous
; __device__ __forceinline__ float bf2f(bf16_t b) { return __uint_as_float(((unsigned)b) << 16); }
; __device__ __forceinline__ float fast_sigmoid(float x) { return __builtin_amdgcn_rcpf(1.0f + __builtin_amdgcn_exp2f(-1.4426950408889634f * x)); }
; template <int DIR>
; __device__ __forceinline__ void scan_dir(PP p, const bf16_t* xs, const ScanW& w, ScanW& wn, int ndir, int nct, bool do_next, int n, int ct, int l31, int hl, int id, int rowbase, bool latent, float (&hf)[2][16]) {
;     ...
;     for (int rt = 0; rt < 2; ++rt) {
;         bf16x8 af[4];
; #pragma unroll
;         for (int st = 0; st < 4; ++st) af[st] = *(const bf16x8*)(xs + (32 * rt + l31) * XS + 64 * n + 16 * st + 8 * hl);
;         f32x16 ga, gi;
; #pragma unroll
;         for (int i = 0; i < 16; ++i) { ga[i] = 0.f; gi[i] = 0.f; }
; #pragma unroll
;         for (int st = 0; st < 4; ++st) { ga = __builtin_amdgcn_mfma_f32_32x32x16_bf16(af[st], wfa[st], ga, 0, 0, 0); gi = __builtin_amdgcn_mfma_f32_32x32x16_bf16(af[st], wfi[st], gi, 0, 0, 0); }
; #pragma unroll
;         for (int i = 0; i < 16; ++i) {
;             const int token = 32 * rt + 8 * (i >> 2) + 4 * hl + (i & 3);
;             const float xv = bf2f(xs[token * XS + ch]);
;             const float rr = fast_sigmoid(ga[i] + ba), ii = fast_sigmoid(gi[i] + bi);
;             const float la2 = rr * sp8l2;
;             const float av = __builtin_amdgcn_exp2f(la2);
;             const float t2 = la2 * 1.3862943611f;
;             float em1p = t2 * (1.0f + t2 * (0.5f + t2 * (0.16666667f + t2 * (0.041666668f + t2 * 0.0083333333f)))), em1e = __builtin_fmaf(av, av, -1.0f);
;             asm volatile("" : "+v"(em1p), "+v"(em1e));
;             const float em1 = (t2 > -0.1f) ? em1p : em1e;
;             a[rt][i] = av; u[rt][i] = __builtin_amdgcn_sqrtf(-em1) * (ii * xv);
;         }
.LBB0_378:
	ds_read_b128 v[2:5], v187
	s_lshl_b32 s48, s80, 5
	v_or_b32_e32 v66, s48, v150
	v_lshl_add_u32 v42, v66, 1, 0
	v_add_u32_e32 v0, v42, v151
	ds_read_u16 v43, v0
	ds_read_b128 v[34:37], v187 offset:32
	ds_read_b128 v[38:41], v187 offset:64
	s_waitcnt vmcnt(7) lgkmcnt(3)
	v_mfma_f32_32x32x16_bf16 v[18:33], v[2:5], v[114:117], 0
	s_waitcnt vmcnt(2)
	v_mfma_f32_32x32x16_bf16 v[2:17], v[2:5], v[134:137], 0
	s_waitcnt lgkmcnt(1)
	v_mfma_f32_32x32x16_bf16 v[18:33], v[34:37], v[118:121], v[18:33]
	v_mfma_f32_32x32x16_bf16 v[2:17], v[34:37], v[126:129], v[2:17]
	ds_read_b128 v[34:37], v187 offset:96
	s_waitcnt lgkmcnt(1)
	v_mfma_f32_32x32x16_bf16 v[18:33], v[38:41], v[122:125], v[18:33]
	s_waitcnt vmcnt(1) lgkmcnt(0)
	ds_read_u16 v82, v0 offset:1040
	ds_read_u16 v83, v0 offset:2080
	ds_read_u16 v84, v0 offset:3120
	v_add_u32_e32 v113, v42, v152
	ds_read_u16 v85, v113
	ds_read_u16 v86, v0 offset:9360
	ds_read_u16 v87, v0 offset:10400
	ds_read_u16 v88, v0 offset:11440
	ds_read_u16 v89, v113 offset:8320
	ds_read_u16 v90, v0 offset:17680
	ds_read_u16 v91, v0 offset:18720
	ds_read_u16 v92, v0 offset:19760
	ds_read_u16 v93, v0 offset:34320
	ds_read_u16 v94, v0 offset:35360
	ds_read_u16 v95, v0 offset:36400
	ds_read_u16 v96, v0 offset:41600
	ds_read_u16 v97, v0 offset:42640
	ds_read_u16 v98, v0 offset:43680
	ds_read_u16 v99, v0 offset:44720
	ds_read_u16 v100, v0 offset:49920
	ds_read_u16 v101, v0 offset:50960
	ds_read_u16 v102, v0 offset:52000
	ds_read_u16 v103, v0 offset:53040
	ds_read_u16 v104, v0 offset:58240
	ds_read_u16 v105, v0 offset:59280
	ds_read_u16 v106, v0 offset:60320
	v_mfma_f32_32x32x16_bf16 v[18:33], v[34:37], v[138:141], v[18:33]
	v_mfma_f32_32x32x16_bf16 v[2:17], v[38:41], v[130:133], v[2:17]
	s_nop 10
	v_add_f32_e32 v18, v192, v18
	v_mul_f32_e32 v18, 0xbfb8aa3b, v18
	v_exp_f32_e32 v18, v18
	v_add_f32_e32 v19, v192, v19
	v_mul_f32_e32 v19, 0xbfb8aa3b, v19
	v_exp_f32_e32 v19, v19
	v_add_f32_e32 v18, 1.0, v18
	s_waitcnt vmcnt(0)
	v_mfma_f32_32x32x16_bf16 v[2:17], v[34:37], v[142:145], v[2:17]
	v_rcp_f32_e32 v18, v18
	v_add_f32_e32 v19, 1.0, v19
	v_rcp_f32_e32 v19, v19
	v_lshlrev_b32_e32 v34, 16, v43
	v_mul_f32_e32 v18, v194, v18
	v_exp_f32_e32 v50, v18
	v_mul_f32_e32 v18, 0x3fb17218, v18
	s_nop 4
	v_add_f32_e32 v2, v191, v2
	v_mul_f32_e32 v2, 0xbfb8aa3b, v2
	v_exp_f32_e32 v2, v2
	v_fmamk_f32 v35, v18, 0x3c088888, v186
	v_fmaak_f32 v35, v18, v35, 0x3e2aaaab
	v_fma_f32 v35, v18, v35, 0.5
	v_add_f32_e32 v2, 1.0, v2
	v_add_f32_e32 v3, v191, v3
	v_rcp_f32_e32 v2, v2
	v_fma_f32 v35, v18, v35, 1.0
	v_mul_f32_e32 v3, 0xbfb8aa3b, v3
	v_mul_f32_e32 v35, v18, v35
	v_fma_f32 v36, v50, v50, -1.0
	v_exp_f32_e32 v3, v3
	v_mul_f32_e32 v19, v194, v19
	v_cmp_lt_f32_e32 vcc, s76, v18
	v_exp_f32_e32 v52, v19
	v_mul_f32_e32 v19, 0x3fb17218, v19
	v_cndmask_b32_e32 v18, v36, v35, vcc
	v_fmamk_f32 v35, v19, 0x3c088888, v186
	v_mul_f32_e32 v2, v2, v34
	v_fmaak_f32 v35, v19, v35, 0x3e2aaaab
	v_sqrt_f32_e64 v18, -v18
	v_add_f32_e32 v3, 1.0, v3
	v_fma_f32 v35, v19, v35, 0.5
	v_add_f32_e32 v4, v191, v4
	v_rcp_f32_e32 v3, v3
	v_fma_f32 v35, v19, v35, 1.0
	v_mul_f32_e32 v4, 0xbfb8aa3b, v4
	v_mul_f32_e32 v35, v19, v35
	v_fma_f32 v36, v52, v52, -1.0
	v_cmp_lt_f32_e32 vcc, s76, v19
	v_exp_f32_e32 v4, v4
	v_mul_f32_e32 v2, v2, v18
	v_cndmask_b32_e32 v19, v36, v35, vcc
	v_sqrt_f32_e64 v19, -v19
	s_waitcnt lgkmcnt(0)
	v_lshlrev_b32_e32 v18, 16, v82
	v_mul_f32_e32 v3, v3, v18
	v_add_f32_e32 v4, 1.0, v4
	v_rcp_f32_e32 v4, v4
	v_mul_f32_e32 v3, v3, v19
	v_add_f32_e32 v19, v192, v20
	v_mul_f32_e32 v19, 0xbfb8aa3b, v19
	v_exp_f32_e32 v19, v19
	s_waitcnt lgkmcnt(0)
	v_lshlrev_b32_e32 v18, 16, v83
	v_mul_f32_e32 v4, v4, v18
	v_add_f32_e32 v18, v192, v21
	v_mul_f32_e32 v18, 0xbfb8aa3b, v18
	v_exp_f32_e32 v18, v18
	v_add_f32_e32 v19, 1.0, v19
	v_rcp_f32_e32 v19, v19
	v_add_f32_e32 v5, v191, v5
	v_add_f32_e32 v18, 1.0, v18
	v_rcp_f32_e32 v18, v18
	v_mul_f32_e32 v19, v194, v19
	v_exp_f32_e32 v51, v19
	v_mul_f32_e32 v19, 0x3fb17218, v19
	v_fmamk_f32 v20, v19, 0x3c088888, v186
	v_fmaak_f32 v20, v19, v20, 0x3e2aaaab
	v_mul_f32_e32 v18, v194, v18
	v_fma_f32 v20, v19, v20, 0.5
	v_mul_f32_e32 v5, 0xbfb8aa3b, v5
	v_exp_f32_e32 v54, v18
	v_mul_f32_e32 v18, 0x3fb17218, v18
	v_fma_f32 v20, v19, v20, 1.0
	v_exp_f32_e32 v5, v5
	v_fmamk_f32 v21, v18, 0x3c088888, v186
	v_mul_f32_e32 v20, v19, v20
	v_fma_f32 v34, v51, v51, -1.0
	v_fmaak_f32 v21, v18, v21, 0x3e2aaaab
	v_cmp_lt_f32_e32 vcc, s76, v19
	v_fma_f32 v21, v18, v21, 0.5
	v_fma_f32 v21, v18, v21, 1.0
	v_cndmask_b32_e32 v19, v34, v20, vcc
	v_sqrt_f32_e64 v19, -v19
	v_add_f32_e32 v5, 1.0, v5
	v_mul_f32_e32 v21, v18, v21
	v_fma_f32 v34, v54, v54, -1.0
	v_cmp_lt_f32_e32 vcc, s76, v18
	v_rcp_f32_e32 v5, v5
	v_add_f32_e32 v6, v191, v6
	v_cndmask_b32_e32 v18, v34, v21, vcc
	v_sqrt_f32_e64 v18, -v18
	v_mul_f32_e32 v6, 0xbfb8aa3b, v6
	v_mul_f32_e32 v4, v4, v19
	s_waitcnt lgkmcnt(0)
	v_lshlrev_b32_e32 v19, 16, v84
	v_exp_f32_e32 v6, v6
	v_mul_f32_e32 v5, v5, v19
	v_mul_f32_e32 v5, v18, v5
	v_add_u32_e32 v18, v42, v152
	v_add_f32_e32 v20, v192, v22
	v_mul_f32_e32 v20, 0xbfb8aa3b, v20
	v_add_f32_e32 v6, 1.0, v6
	v_exp_f32_e32 v20, v20
	v_rcp_f32_e32 v6, v6
	s_waitcnt lgkmcnt(0)
; __device__ __forceinline__ float bf2f(bf16_t b) { return __uint_as_float(((unsigned)b) << 16); }
; __device__ __forceinline__ float fast_sigmoid(float x) { return __builtin_amdgcn_rcpf(1.0f + __builtin_amdgcn_exp2f(-1.4426950408889634f * x)); }
; template <int DIR>
; __device__ __forceinline__ void scan_dir(PP p, const bf16_t* xs, const ScanW& w, ScanW& wn, int ndir, int nct, bool do_next, int n, int ct, int l31, int hl, int id, int rowbase, bool latent, float (&hf)[2][16]) {
;     ...
;         for (int i = 0; i < 16; ++i) {
;             const int token = 32 * rt + 8 * (i >> 2) + 4 * hl + (i & 3);
;             const float xv = bf2f(xs[token * XS + ch]);
;             const float rr = fast_sigmoid(ga[i] + ba), ii = fast_sigmoid(gi[i] + bi);
;             const float la2 = rr * sp8l2;
;             const float av = __builtin_amdgcn_exp2f(la2);
;             const float t2 = la2 * 1.3862943611f;
;             float em1p = t2 * (1.0f + t2 * (0.5f + t2 * (0.16666667f + t2 * (0.041666668f + t2 * 0.0083333333f)))), em1e = __builtin_fmaf(av, av, -1.0f);
;             asm volatile("" : "+v"(em1p), "+v"(em1e));
;             const float em1 = (t2 > -0.1f) ? em1p : em1e;
;             a[rt][i] = av; u[rt][i] = __builtin_amdgcn_sqrtf(-em1) * (ii * xv);
;         }
	v_lshlrev_b32_e32 v19, 16, v85
	v_add_f32_e32 v7, v191, v7
	v_add_f32_e32 v20, 1.0, v20
	v_mul_f32_e32 v6, v6, v19
	v_add_f32_e32 v19, v192, v23
	v_rcp_f32_e32 v20, v20
	v_mul_f32_e32 v19, 0xbfb8aa3b, v19
	v_exp_f32_e32 v19, v19
	v_mul_f32_e32 v7, 0xbfb8aa3b, v7
	v_mul_f32_e32 v20, v194, v20
	v_exp_f32_e32 v53, v20
	v_mul_f32_e32 v20, 0x3fb17218, v20
	v_add_f32_e32 v19, 1.0, v19
	v_fmamk_f32 v21, v20, 0x3c088888, v186
	v_rcp_f32_e32 v19, v19
	v_fmaak_f32 v21, v20, v21, 0x3e2aaaab
	v_fma_f32 v21, v20, v21, 0.5
	v_fma_f32 v21, v20, v21, 1.0
	v_mul_f32_e32 v21, v20, v21
	v_fma_f32 v22, v53, v53, -1.0
	v_mul_f32_e32 v19, v194, v19
	v_cmp_lt_f32_e32 vcc, s76, v20
	v_exp_f32_e32 v55, v19
	v_mul_f32_e32 v19, 0x3fb17218, v19
	v_cndmask_b32_e32 v20, v22, v21, vcc
	v_exp_f32_e32 v7, v7
	v_fmamk_f32 v22, v19, 0x3c088888, v186
	v_fmaak_f32 v22, v19, v22, 0x3e2aaaab
	v_fma_f32 v22, v19, v22, 0.5
	v_fma_f32 v22, v19, v22, 1.0
	v_sqrt_f32_e64 v20, -v20
	v_add_f32_e32 v7, 1.0, v7
	v_mul_f32_e32 v22, v19, v22
	v_fma_f32 v23, v55, v55, -1.0
	v_cmp_lt_f32_e32 vcc, s76, v19
	v_rcp_f32_e32 v7, v7
	v_add_f32_e32 v8, v191, v8
	v_cndmask_b32_e32 v19, v23, v22, vcc
	v_sqrt_f32_e64 v19, -v19
	v_mul_f32_e32 v8, 0xbfb8aa3b, v8
	v_exp_f32_e32 v8, v8
	v_mul_f32_e32 v6, v20, v6
	s_waitcnt lgkmcnt(0)
	v_lshlrev_b32_e32 v20, 16, v86
	v_mul_f32_e32 v7, v7, v20
	v_mul_f32_e32 v7, v19, v7
	v_add_f32_e32 v20, v192, v24
	v_mul_f32_e32 v20, 0xbfb8aa3b, v20
	v_add_f32_e32 v8, 1.0, v8
	v_exp_f32_e32 v20, v20
	v_rcp_f32_e32 v8, v8
	s_waitcnt lgkmcnt(0)
	v_lshlrev_b32_e32 v19, 16, v87
	v_add_f32_e32 v9, v191, v9
	v_add_f32_e32 v20, 1.0, v20
	v_mul_f32_e32 v8, v8, v19
	v_add_f32_e32 v19, v192, v25
	v_rcp_f32_e32 v20, v20
	v_mul_f32_e32 v19, 0xbfb8aa3b, v19
	v_exp_f32_e32 v19, v19
	v_mul_f32_e32 v9, 0xbfb8aa3b, v9
	v_mul_f32_e32 v20, v194, v20
	v_exp_f32_e32 v67, v20
	v_mul_f32_e32 v20, 0x3fb17218, v20
	v_add_f32_e32 v19, 1.0, v19
	v_fmamk_f32 v21, v20, 0x3c088888, v186
	v_rcp_f32_e32 v19, v19
	v_fmaak_f32 v21, v20, v21, 0x3e2aaaab
	v_fma_f32 v21, v20, v21, 0.5
	v_fma_f32 v21, v20, v21, 1.0
	v_mul_f32_e32 v21, v20, v21
	v_fma_f32 v22, v67, v67, -1.0
	v_mul_f32_e32 v19, v194, v19
	v_cmp_lt_f32_e32 vcc, s76, v20
	v_exp_f32_e32 v69, v19
	v_mul_f32_e32 v19, 0x3fb17218, v19
	v_cndmask_b32_e32 v20, v22, v21, vcc
	v_exp_f32_e32 v9, v9
	v_fmamk_f32 v22, v19, 0x3c088888, v186
	v_fmaak_f32 v22, v19, v22, 0x3e2aaaab
	v_fma_f32 v22, v19, v22, 0.5
	v_fma_f32 v22, v19, v22, 1.0
	v_sqrt_f32_e64 v20, -v20
	v_add_f32_e32 v9, 1.0, v9
	v_mul_f32_e32 v22, v19, v22
	v_fma_f32 v23, v69, v69, -1.0
	v_cmp_lt_f32_e32 vcc, s76, v19
	v_rcp_f32_e32 v9, v9
	v_add_f32_e32 v10, v191, v10
	v_cndmask_b32_e32 v19, v23, v22, vcc
	v_sqrt_f32_e64 v19, -v19
	v_mul_f32_e32 v10, 0xbfb8aa3b, v10
	v_exp_f32_e32 v10, v10
	v_mul_f32_e32 v8, v20, v8
	s_waitcnt lgkmcnt(0)
	v_lshlrev_b32_e32 v20, 16, v88
	v_mul_f32_e32 v9, v9, v20
	v_mul_f32_e32 v76, v19, v9
	v_add_f32_e32 v19, v192, v26
	v_mul_f32_e32 v19, 0xbfb8aa3b, v19
	v_add_f32_e32 v10, 1.0, v10
	v_exp_f32_e32 v19, v19
	v_rcp_f32_e32 v10, v10
	s_waitcnt lgkmcnt(0)
	v_lshlrev_b32_e32 v9, 16, v89
	v_add_f32_e32 v11, v191, v11
	v_add_f32_e32 v19, 1.0, v19
	v_mul_f32_e32 v9, v10, v9
	v_add_f32_e32 v10, v192, v27
	v_rcp_f32_e32 v19, v19
	v_mul_f32_e32 v10, 0xbfb8aa3b, v10
	v_exp_f32_e32 v10, v10
	v_mul_f32_e32 v11, 0xbfb8aa3b, v11
	v_mul_f32_e32 v19, v194, v19
	v_exp_f32_e32 v68, v19
	v_mul_f32_e32 v19, 0x3fb17218, v19
	v_add_f32_e32 v10, 1.0, v10
	v_fmamk_f32 v20, v19, 0x3c088888, v186
	v_rcp_f32_e32 v10, v10
	v_fmaak_f32 v20, v19, v20, 0x3e2aaaab
	v_fma_f32 v20, v19, v20, 0.5
	v_fma_f32 v20, v19, v20, 1.0
	v_mul_f32_e32 v20, v19, v20
	v_fma_f32 v21, v68, v68, -1.0
	v_mul_f32_e32 v10, v194, v10
	v_cmp_lt_f32_e32 vcc, s76, v19
	v_exp_f32_e32 v71, v10
	v_mul_f32_e32 v10, 0x3fb17218, v10
	v_cndmask_b32_e32 v19, v21, v20, vcc
	v_exp_f32_e32 v11, v11
	v_fmamk_f32 v21, v10, 0x3c088888, v186
	v_fmaak_f32 v21, v10, v21, 0x3e2aaaab
	v_fma_f32 v21, v10, v21, 0.5
	v_fma_f32 v21, v10, v21, 1.0
	v_sqrt_f32_e64 v19, -v19
	v_add_f32_e32 v11, 1.0, v11
	v_mul_f32_e32 v21, v10, v21
	v_fma_f32 v22, v71, v71, -1.0
	v_cmp_lt_f32_e32 vcc, s76, v10
	v_rcp_f32_e32 v11, v11
	v_mul_f32_e32 v74, v19, v9
	v_cndmask_b32_e32 v10, v22, v21, vcc
	v_sqrt_f32_e64 v10, -v10
	s_waitcnt lgkmcnt(0)
	v_lshlrev_b32_e32 v9, 16, v90
	v_mul_f32_e32 v9, v11, v9
	v_add_f32_e32 v11, v191, v12
	v_mul_f32_e32 v73, v10, v9
	v_add_f32_e32 v10, v192, v28
	v_mul_f32_e32 v10, 0xbfb8aa3b, v10
	v_exp_f32_e32 v10, v10
	v_mul_f32_e32 v11, 0xbfb8aa3b, v11
	v_exp_f32_e32 v11, v11
	v_add_f32_e32 v10, 1.0, v10
	v_rcp_f32_e32 v10, v10
	s_waitcnt lgkmcnt(0)
; __device__ __forceinline__ float bf2f(bf16_t b) { return __uint_as_float(((unsigned)b) << 16); }
; __device__ __forceinline__ float fast_sigmoid(float x) { return __builtin_amdgcn_rcpf(1.0f + __builtin_amdgcn_exp2f(-1.4426950408889634f * x)); }
; template <int DIR>
; __device__ __forceinline__ void scan_dir(PP p, const bf16_t* xs, const ScanW& w, ScanW& wn, int ndir, int nct, bool do_next, int n, int ct, int l31, int hl, int id, int rowbase, bool latent, float (&hf)[2][16]) {
;     ...
;     for (int rt = 0; rt < 2; ++rt) {
;         bf16x8 af[4];
; #pragma unroll
;         for (int st = 0; st < 4; ++st) af[st] = *(const bf16x8*)(xs + (32 * rt + l31) * XS + 64 * n + 16 * st + 8 * hl);
;         f32x16 ga, gi;
; #pragma unroll
;         for (int i = 0; i < 16; ++i) { ga[i] = 0.f; gi[i] = 0.f; }
; #pragma unroll
;         for (int st = 0; st < 4; ++st) { ga = __builtin_amdgcn_mfma_f32_32x32x16_bf16(af[st], wfa[st], ga, 0, 0, 0); gi = __builtin_amdgcn_mfma_f32_32x32x16_bf16(af[st], wfi[st], gi, 0, 0, 0); }
; #pragma unroll
;         for (int i = 0; i < 16; ++i) {
;             const int token = 32 * rt + 8 * (i >> 2) + 4 * hl + (i & 3);
;             const float xv = bf2f(xs[token * XS + ch]);
;             const float rr = fast_sigmoid(ga[i] + ba), ii = fast_sigmoid(gi[i] + bi);
;             const float la2 = rr * sp8l2;
;             const float av = __builtin_amdgcn_exp2f(la2);
;             const float t2 = la2 * 1.3862943611f;
;             float em1p = t2 * (1.0f + t2 * (0.5f + t2 * (0.16666667f + t2 * (0.041666668f + t2 * 0.0083333333f)))), em1e = __builtin_fmaf(av, av, -1.0f);
;             asm volatile("" : "+v"(em1p), "+v"(em1e));
;             const float em1 = (t2 > -0.1f) ? em1p : em1e;
;             a[rt][i] = av; u[rt][i] = __builtin_amdgcn_sqrtf(-em1) * (ii * xv);
;         }
	v_lshlrev_b32_e32 v9, 16, v91
	v_add_f32_e32 v11, 1.0, v11
	v_rcp_f32_e32 v11, v11
	v_mul_f32_e32 v10, v194, v10
	v_exp_f32_e32 v70, v10
	v_mul_f32_e32 v10, 0x3fb17218, v10
	v_fmamk_f32 v12, v10, 0x3c088888, v186
	v_fmaak_f32 v12, v10, v12, 0x3e2aaaab
	v_fma_f32 v12, v10, v12, 0.5
	v_fma_f32 v12, v10, v12, 1.0
	v_mul_f32_e32 v12, v10, v12
	v_fma_f32 v19, v70, v70, -1.0
	v_cmp_lt_f32_e32 vcc, s76, v10
	v_mul_f32_e32 v9, v11, v9
	v_add_f32_e32 v11, v191, v13
	v_cndmask_b32_e32 v10, v19, v12, vcc
	v_add_f32_e32 v12, v192, v29
	v_mul_f32_e32 v12, 0xbfb8aa3b, v12
	v_exp_f32_e32 v12, v12
	v_sqrt_f32_e64 v19, -v10
	v_mul_f32_e32 v11, 0xbfb8aa3b, v11
	v_exp_f32_e32 v21, v11
	v_add_f32_e32 v10, 1.0, v12
	v_rcp_f32_e32 v10, v10
	v_add_f32_e32 v11, v192, v30
	v_mul_f32_e32 v11, 0xbfb8aa3b, v11
	v_exp_f32_e32 v11, v11
	v_mul_f32_e32 v10, v194, v10
	v_mul_f32_e32 v22, 0x3fb17218, v10
	v_exp_f32_e32 v75, v10
	v_fmamk_f32 v10, v22, 0x3c088888, v186
	v_fmaak_f32 v10, v22, v10, 0x3e2aaaab
	v_fma_f32 v10, v22, v10, 0.5
	v_fma_f32 v10, v22, v10, 1.0
	v_mul_f32_e32 v23, v22, v10
	v_add_f32_e32 v10, 1.0, v11
	v_rcp_f32_e32 v10, v10
	v_add_f32_e32 v11, v192, v31
	v_mul_f32_e32 v11, 0xbfb8aa3b, v11
	v_exp_f32_e32 v11, v11
	v_mul_f32_e32 v10, v194, v10
	v_mul_f32_e32 v60, 0x3fb17218, v10
	v_exp_f32_e32 v72, v10
	v_fmamk_f32 v10, v60, 0x3c088888, v186
	v_fmaak_f32 v10, v60, v10, 0x3e2aaaab
	v_fma_f32 v10, v60, v10, 0.5
	v_fma_f32 v10, v60, v10, 1.0
	v_mul_f32_e32 v61, v60, v10
	v_add_f32_e32 v10, 1.0, v11
	v_rcp_f32_e32 v10, v10
	v_add_f32_e32 v11, v192, v32
	v_mul_f32_e32 v11, 0xbfb8aa3b, v11
	v_exp_f32_e32 v11, v11
	v_mul_f32_e32 v10, v194, v10
	v_mul_f32_e32 v64, 0x3fb17218, v10
	v_exp_f32_e32 v78, v10
	v_fmamk_f32 v10, v64, 0x3c088888, v186
	v_fmaak_f32 v10, v64, v10, 0x3e2aaaab
	v_fma_f32 v10, v64, v10, 0.5
	v_fma_f32 v10, v64, v10, 1.0
	v_mul_f32_e32 v65, v64, v10
	v_add_f32_e32 v10, 1.0, v11
	v_rcp_f32_e32 v10, v10
	v_add_f32_e32 v11, v192, v33
	v_mul_f32_e32 v11, 0xbfb8aa3b, v11
	v_exp_f32_e32 v11, v11
	v_mul_f32_e32 v10, v194, v10
	v_mul_f32_e32 v146, 0x3fb17218, v10
	v_exp_f32_e32 v77, v10
	v_fmamk_f32 v10, v146, 0x3c088888, v186
	v_fmaak_f32 v10, v146, v10, 0x3e2aaaab
	v_fma_f32 v10, v146, v10, 0.5
	v_fma_f32 v10, v146, v10, 1.0
	v_mul_f32_e32 v147, v146, v10
	v_add_f32_e32 v10, 1.0, v11
	v_rcp_f32_e32 v10, v10
	v_fma_f32 v24, v75, v75, -1.0
	v_mul_f32_e32 v209, v19, v9
	v_mul_f32_e32 v10, v194, v10
	v_mul_f32_e32 v156, 0x3fb17218, v10
	v_add_f32_e32 v19, 1.0, v21
	v_cmp_lt_f32_e32 vcc, s76, v22
	v_exp_f32_e32 v79, v10
	v_fmamk_f32 v10, v156, 0x3c088888, v186
	v_rcp_f32_e32 v35, v19
	v_cndmask_b32_e32 v19, v24, v23, vcc
	v_fmaak_f32 v10, v156, v10, 0x3e2aaaab
	v_sqrt_f32_e64 v36, -v19
	v_fma_f32 v10, v156, v10, 0.5
	v_fma_f32 v10, v156, v10, 1.0
	s_waitcnt lgkmcnt(0)
	v_lshlrev_b32_e32 v9, 16, v92
	v_fma_f32 v62, v72, v72, -1.0
	v_fma_f32 v80, v78, v78, -1.0
	v_fma_f32 v154, v77, v77, -1.0
	v_mul_f32_e32 v158, v156, v10
	v_fma_f32 v159, v79, v79, -1.0
	v_mul_f32_e32 v9, v35, v9
	ds_read_u16 v34, v18 offset:16640
	ds_read_u16 v63, v0 offset:26000
	ds_read_u16 v81, v0 offset:27040
	ds_read_u16 v155, v0 offset:28080
	ds_read_b128 v[10:13], v187 offset:33280
	ds_read_u16 v195, v18 offset:24960
	v_mul_f32_e32 v217, v36, v9
	v_add_f32_e32 v9, v191, v14
	v_mul_f32_e32 v9, 0xbfb8aa3b, v9
	v_exp_f32_e32 v9, v9
	v_add_f32_e32 v15, v191, v15
	v_mul_f32_e32 v15, 0xbfb8aa3b, v15
	v_exp_f32_e32 v15, v15
	v_add_f32_e32 v9, 1.0, v9
	v_rcp_f32_e32 v9, v9
	ds_read_b128 v[56:59], v187 offset:33312
	s_waitcnt lgkmcnt(6)
	v_lshlrev_b32_e32 v14, 16, v34
	s_waitcnt lgkmcnt(2)
	v_mfma_f32_32x32x16_bf16 v[34:49], v[10:13], v[134:137], 0
	v_cmp_lt_f32_e32 vcc, s76, v60
	v_mul_f32_e32 v9, v9, v14
	v_add_f32_e32 v14, 1.0, v15
	v_rcp_f32_e32 v14, v14
	v_mfma_f32_32x32x16_bf16 v[18:33], v[10:13], v[114:117], 0
	v_cndmask_b32_e32 v10, v62, v61, vcc
	v_sqrt_f32_e64 v60, -v10
	ds_read_b128 v[10:13], v187 offset:33344
	v_cmp_lt_f32_e32 vcc, s76, v64
	v_mul_f32_e32 v197, v60, v9
	v_lshlrev_b32_e32 v9, 16, v63
	v_mul_f32_e32 v9, v14, v9
	v_add_f32_e32 v14, v191, v16
	s_waitcnt lgkmcnt(1)
	v_mfma_f32_32x32x16_bf16 v[34:49], v[56:59], v[126:129], v[34:49]
	v_mul_f32_e32 v14, 0xbfb8aa3b, v14
	v_exp_f32_e32 v14, v14
	v_cndmask_b32_e32 v15, v80, v65, vcc
	v_sqrt_f32_e64 v15, -v15
	v_cmp_lt_f32_e32 vcc, s76, v146
	v_add_f32_e32 v14, 1.0, v14
	v_mul_f32_e32 v199, v15, v9
	v_mfma_f32_32x32x16_bf16 v[18:33], v[56:59], v[118:121], v[18:33]
	v_rcp_f32_e32 v56, v14
	v_add_f32_e32 v14, v191, v17
	v_mul_f32_e32 v57, 0xbfb8aa3b, v14
	ds_read_b128 v[14:17], v187 offset:33376
	v_lshlrev_b32_e32 v9, 16, v81
	v_mul_f32_e32 v9, v56, v9
	s_waitcnt lgkmcnt(1)
	v_mfma_f32_32x32x16_bf16 v[34:49], v[10:13], v[130:133], v[34:49]
	v_mfma_f32_32x32x16_bf16 v[18:33], v[10:13], v[122:125], v[18:33]
	v_exp_f32_e32 v10, v57
	v_cndmask_b32_e32 v11, v154, v147, vcc
	v_sqrt_f32_e64 v11, -v11
	v_cmp_lt_f32_e32 vcc, s76, v156
	v_add_f32_e32 v10, 1.0, v10
	v_rcp_f32_e32 v10, v10
	v_cndmask_b32_e32 v12, v159, v158, vcc
	s_waitcnt lgkmcnt(0)
; __device__ __forceinline__ float bf2f(bf16_t b) { return __uint_as_float(((unsigned)b) << 16); }
; __device__ __forceinline__ float fast_sigmoid(float x) { return __builtin_amdgcn_rcpf(1.0f + __builtin_amdgcn_exp2f(-1.4426950408889634f * x)); }
; template <int DIR>
; __device__ __forceinline__ void scan_dir(PP p, const bf16_t* xs, const ScanW& w, ScanW& wn, int ndir, int nct, bool do_next, int n, int ct, int l31, int hl, int id, int rowbase, bool latent, float (&hf)[2][16]) {
;     ...
;         for (int i = 0; i < 16; ++i) {
;             const int token = 32 * rt + 8 * (i >> 2) + 4 * hl + (i & 3);
;             const float xv = bf2f(xs[token * XS + ch]);
;             const float rr = fast_sigmoid(ga[i] + ba), ii = fast_sigmoid(gi[i] + bi);
;             const float la2 = rr * sp8l2;
;             const float av = __builtin_amdgcn_exp2f(la2);
;             const float t2 = la2 * 1.3862943611f;
;             float em1p = t2 * (1.0f + t2 * (0.5f + t2 * (0.16666667f + t2 * (0.041666668f + t2 * 0.0083333333f)))), em1e = __builtin_fmaf(av, av, -1.0f);
;             asm volatile("" : "+v"(em1p), "+v"(em1e));
;             const float em1 = (t2 > -0.1f) ? em1p : em1e;
;             a[rt][i] = av; u[rt][i] = __builtin_amdgcn_sqrtf(-em1) * (ii * xv);
;         }
	v_mfma_f32_32x32x16_bf16 v[34:49], v[14:17], v[142:145], v[34:49]
	v_sqrt_f32_e64 v12, -v12
	v_mul_f32_e32 v204, v11, v9
	v_lshlrev_b32_e32 v9, 16, v155
	v_mul_f32_e32 v9, v10, v9
	v_mul_f32_e32 v202, v12, v9
	v_lshlrev_b32_e32 v11, 16, v195
	s_nop 5
	v_add_f32_e32 v10, v191, v34
	v_mfma_f32_32x32x16_bf16 v[18:33], v[14:17], v[138:141], v[18:33]
	v_mul_f32_e32 v10, 0xbfb8aa3b, v10
	v_exp_f32_e32 v10, v10
	s_nop 0
	v_add_f32_e32 v10, 1.0, v10
	v_rcp_f32_e32 v10, v10
	s_nop 6
	v_add_f32_e32 v9, v192, v18
	v_mul_f32_e32 v9, 0xbfb8aa3b, v9
	v_exp_f32_e32 v9, v9
	v_mul_f32_e32 v10, v10, v11
	v_add_f32_e32 v11, v192, v19
	v_mul_f32_e32 v11, 0xbfb8aa3b, v11
	v_add_f32_e32 v9, 1.0, v9
	v_rcp_f32_e32 v9, v9
	v_exp_f32_e32 v11, v11
	v_mul_f32_e32 v9, v194, v9
	v_exp_f32_e32 v80, v9
	v_mul_f32_e32 v9, 0x3fb17218, v9
	v_fmamk_f32 v12, v9, 0x3c088888, v186
	v_fmaak_f32 v12, v9, v12, 0x3e2aaaab
	v_add_f32_e32 v11, 1.0, v11
	v_fma_f32 v12, v9, v12, 0.5
	v_rcp_f32_e32 v11, v11
	v_fma_f32 v12, v9, v12, 1.0
	v_mul_f32_e32 v12, v9, v12
	v_fma_f32 v13, v80, v80, -1.0
	v_cmp_lt_f32_e32 vcc, s76, v9
	v_mul_f32_e32 v11, v194, v11
	v_exp_f32_e32 v146, v11
	v_cndmask_b32_e32 v9, v13, v12, vcc
	v_add_f32_e32 v12, v191, v35
	v_mul_f32_e32 v12, 0xbfb8aa3b, v12
	v_mul_f32_e32 v11, 0x3fb17218, v11
	v_exp_f32_e32 v12, v12
	v_fmamk_f32 v14, v11, 0x3c088888, v186
	v_fmaak_f32 v14, v11, v14, 0x3e2aaaab
	v_fma_f32 v14, v11, v14, 0.5
	v_fma_f32 v14, v11, v14, 1.0
	v_sqrt_f32_e64 v9, -v9
	v_add_f32_e32 v12, 1.0, v12
	v_mul_f32_e32 v14, v11, v14
	v_fma_f32 v15, v146, v146, -1.0
	v_cmp_lt_f32_e32 vcc, s76, v11
	v_rcp_f32_e32 v12, v12
	v_mul_f32_e32 v196, v10, v9
	v_cndmask_b32_e32 v11, v15, v14, vcc
	v_sqrt_f32_e64 v11, -v11
	s_waitcnt lgkmcnt(0)
	v_lshlrev_b32_e32 v9, 16, v93
	v_mul_f32_e32 v9, v12, v9
	v_add_f32_e32 v10, v192, v20
	v_mul_f32_e32 v195, v9, v11
	v_add_f32_e32 v11, v191, v36
	v_mul_f32_e32 v11, 0xbfb8aa3b, v11
	v_exp_f32_e32 v11, v11
	v_mul_f32_e32 v10, 0xbfb8aa3b, v10
	v_exp_f32_e32 v10, v10
	v_add_f32_e32 v11, 1.0, v11
	v_rcp_f32_e32 v11, v11
	v_add_f32_e32 v10, 1.0, v10
	v_rcp_f32_e32 v10, v10
	s_waitcnt lgkmcnt(0)
	v_lshlrev_b32_e32 v9, 16, v94
	v_mul_f32_e32 v9, v11, v9
	v_add_f32_e32 v11, v192, v21
	v_mul_f32_e32 v11, 0xbfb8aa3b, v11
	v_exp_f32_e32 v11, v11
	v_mul_f32_e32 v10, v194, v10
	v_exp_f32_e32 v81, v10
	v_mul_f32_e32 v10, 0x3fb17218, v10
	v_fmamk_f32 v12, v10, 0x3c088888, v186
	v_fmaak_f32 v12, v10, v12, 0x3e2aaaab
	v_add_f32_e32 v11, 1.0, v11
	v_fma_f32 v12, v10, v12, 0.5
	v_rcp_f32_e32 v11, v11
	v_fma_f32 v12, v10, v12, 1.0
	v_mul_f32_e32 v12, v10, v12
	v_fma_f32 v13, v81, v81, -1.0
	v_cmp_lt_f32_e32 vcc, s76, v10
	v_mul_f32_e32 v11, v194, v11
	v_exp_f32_e32 v198, v11
	v_cndmask_b32_e32 v10, v13, v12, vcc
	v_add_f32_e32 v12, v191, v37
	v_mul_f32_e32 v12, 0xbfb8aa3b, v12
	v_mul_f32_e32 v11, 0x3fb17218, v11
	v_exp_f32_e32 v12, v12
	v_fmamk_f32 v14, v11, 0x3c088888, v186
	v_fmaak_f32 v14, v11, v14, 0x3e2aaaab
	v_fma_f32 v14, v11, v14, 0.5
	v_fma_f32 v14, v11, v14, 1.0
	v_sqrt_f32_e64 v10, -v10
	v_add_f32_e32 v12, 1.0, v12
	v_mul_f32_e32 v14, v11, v14
	v_fma_f32 v15, v198, v198, -1.0
	v_cmp_lt_f32_e32 vcc, s76, v11
	v_rcp_f32_e32 v12, v12
	v_mul_f32_e32 v214, v9, v10
	v_cndmask_b32_e32 v11, v15, v14, vcc
	v_sqrt_f32_e64 v11, -v11
	s_waitcnt lgkmcnt(0)
	v_lshlrev_b32_e32 v9, 16, v95
	v_mul_f32_e32 v9, v12, v9
	v_add_f32_e32 v10, v192, v22
	v_mul_f32_e32 v211, v11, v9
	v_add_f32_e32 v11, v191, v38
	v_mul_f32_e32 v11, 0xbfb8aa3b, v11
	v_exp_f32_e32 v11, v11
	v_mul_f32_e32 v10, 0xbfb8aa3b, v10
	v_exp_f32_e32 v10, v10
	v_add_f32_e32 v11, 1.0, v11
	v_rcp_f32_e32 v11, v11
	v_add_f32_e32 v10, 1.0, v10
	v_rcp_f32_e32 v10, v10
	s_waitcnt lgkmcnt(0)
	v_lshlrev_b32_e32 v9, 16, v96
	v_mul_f32_e32 v9, v11, v9
	v_add_f32_e32 v11, v192, v23
	v_mul_f32_e32 v11, 0xbfb8aa3b, v11
	v_exp_f32_e32 v11, v11
	v_mul_f32_e32 v10, v194, v10
	v_exp_f32_e32 v147, v10
	v_mul_f32_e32 v10, 0x3fb17218, v10
	v_fmamk_f32 v12, v10, 0x3c088888, v186
	v_fmaak_f32 v12, v10, v12, 0x3e2aaaab
	v_add_f32_e32 v11, 1.0, v11
	v_fma_f32 v12, v10, v12, 0.5
	v_rcp_f32_e32 v11, v11
	v_fma_f32 v12, v10, v12, 1.0
	v_mul_f32_e32 v12, v10, v12
	v_fma_f32 v13, v147, v147, -1.0
	v_cmp_lt_f32_e32 vcc, s76, v10
	v_mul_f32_e32 v11, v194, v11
	v_exp_f32_e32 v201, v11
	v_cndmask_b32_e32 v10, v13, v12, vcc
	v_add_f32_e32 v12, v191, v39
	v_mul_f32_e32 v12, 0xbfb8aa3b, v12
	v_mul_f32_e32 v11, 0x3fb17218, v11
	v_exp_f32_e32 v12, v12
	v_fmamk_f32 v14, v11, 0x3c088888, v186
	v_fmaak_f32 v14, v11, v14, 0x3e2aaaab
	v_fma_f32 v14, v11, v14, 0.5
	v_fma_f32 v14, v11, v14, 1.0
	v_sqrt_f32_e64 v10, -v10
	v_add_f32_e32 v12, 1.0, v12
	v_mul_f32_e32 v14, v11, v14
	v_fma_f32 v15, v201, v201, -1.0
	v_cmp_lt_f32_e32 vcc, s76, v11
	v_rcp_f32_e32 v12, v12
	v_mul_f32_e32 v206, v10, v9
	v_cndmask_b32_e32 v11, v15, v14, vcc
	v_sqrt_f32_e64 v11, -v11
	s_waitcnt lgkmcnt(0)
	v_lshlrev_b32_e32 v9, 16, v97
	v_mul_f32_e32 v9, v12, v9
	v_add_f32_e32 v10, v192, v24
	v_mul_f32_e32 v205, v11, v9
	v_add_f32_e32 v11, v191, v40
	v_mul_f32_e32 v11, 0xbfb8aa3b, v11
	v_exp_f32_e32 v11, v11
	v_mul_f32_e32 v10, 0xbfb8aa3b, v10
	v_exp_f32_e32 v10, v10
	v_add_f32_e32 v11, 1.0, v11
	v_rcp_f32_e32 v11, v11
	v_add_f32_e32 v10, 1.0, v10
	v_rcp_f32_e32 v10, v10
	s_waitcnt lgkmcnt(0)
; __device__ __forceinline__ float bf2f(bf16_t b) { return __uint_as_float(((unsigned)b) << 16); }
; __device__ __forceinline__ float fast_sigmoid(float x) { return __builtin_amdgcn_rcpf(1.0f + __builtin_amdgcn_exp2f(-1.4426950408889634f * x)); }
; template <int DIR>
; __device__ __forceinline__ void scan_dir(PP p, const bf16_t* xs, const ScanW& w, ScanW& wn, int ndir, int nct, bool do_next, int n, int ct, int l31, int hl, int id, int rowbase, bool latent, float (&hf)[2][16]) {
;     ...
;         for (int i = 0; i < 16; ++i) {
;             const int token = 32 * rt + 8 * (i >> 2) + 4 * hl + (i & 3);
;             const float xv = bf2f(xs[token * XS + ch]);
;             const float rr = fast_sigmoid(ga[i] + ba), ii = fast_sigmoid(gi[i] + bi);
;             const float la2 = rr * sp8l2;
;             const float av = __builtin_amdgcn_exp2f(la2);
;             const float t2 = la2 * 1.3862943611f;
;             float em1p = t2 * (1.0f + t2 * (0.5f + t2 * (0.16666667f + t2 * (0.041666668f + t2 * 0.0083333333f)))), em1e = __builtin_fmaf(av, av, -1.0f);
;             asm volatile("" : "+v"(em1p), "+v"(em1e));
;             const float em1 = (t2 > -0.1f) ? em1p : em1e;
;             a[rt][i] = av; u[rt][i] = __builtin_amdgcn_sqrtf(-em1) * (ii * xv);
;         }
	v_lshlrev_b32_e32 v9, 16, v98
	v_mul_f32_e32 v9, v11, v9
	v_add_f32_e32 v11, v192, v25
	v_mul_f32_e32 v11, 0xbfb8aa3b, v11
	v_exp_f32_e32 v11, v11
	v_mul_f32_e32 v10, v194, v10
	v_exp_f32_e32 v200, v10
	v_mul_f32_e32 v10, 0x3fb17218, v10
	v_fmamk_f32 v12, v10, 0x3c088888, v186
	v_fmaak_f32 v12, v10, v12, 0x3e2aaaab
	v_add_f32_e32 v11, 1.0, v11
	v_fma_f32 v12, v10, v12, 0.5
	v_rcp_f32_e32 v11, v11
	v_fma_f32 v12, v10, v12, 1.0
	v_mul_f32_e32 v12, v10, v12
	v_fma_f32 v13, v200, v200, -1.0
	v_cmp_lt_f32_e32 vcc, s76, v10
	v_mul_f32_e32 v11, v194, v11
	v_exp_f32_e32 v207, v11
	v_cndmask_b32_e32 v10, v13, v12, vcc
	v_add_f32_e32 v12, v191, v41
	v_mul_f32_e32 v12, 0xbfb8aa3b, v12
	v_mul_f32_e32 v11, 0x3fb17218, v11
	v_exp_f32_e32 v12, v12
	v_fmamk_f32 v14, v11, 0x3c088888, v186
	v_fmaak_f32 v14, v11, v14, 0x3e2aaaab
	v_fma_f32 v14, v11, v14, 0.5
	v_fma_f32 v14, v11, v14, 1.0
	v_sqrt_f32_e64 v10, -v10
	v_add_f32_e32 v12, 1.0, v12
	v_mul_f32_e32 v14, v11, v14
	v_fma_f32 v15, v207, v207, -1.0
	v_cmp_lt_f32_e32 vcc, s76, v11
	v_rcp_f32_e32 v12, v12
	v_mul_f32_e32 v222, v10, v9
	v_cndmask_b32_e32 v11, v15, v14, vcc
	v_sqrt_f32_e64 v11, -v11
	s_waitcnt lgkmcnt(0)
	v_lshlrev_b32_e32 v9, 16, v99
	v_mul_f32_e32 v9, v12, v9
	v_add_f32_e32 v10, v192, v26
	v_mul_f32_e32 v221, v11, v9
	v_add_f32_e32 v11, v191, v42
	v_mul_f32_e32 v11, 0xbfb8aa3b, v11
	v_exp_f32_e32 v11, v11
	v_mul_f32_e32 v10, 0xbfb8aa3b, v10
	v_exp_f32_e32 v10, v10
	v_add_f32_e32 v11, 1.0, v11
	v_rcp_f32_e32 v11, v11
	v_add_f32_e32 v10, 1.0, v10
	v_rcp_f32_e32 v10, v10
	s_waitcnt lgkmcnt(0)
	v_lshlrev_b32_e32 v9, 16, v100
	v_mul_f32_e32 v9, v11, v9
	v_add_f32_e32 v11, v192, v27
	v_mul_f32_e32 v11, 0xbfb8aa3b, v11
	v_exp_f32_e32 v11, v11
	v_mul_f32_e32 v10, v194, v10
	v_exp_f32_e32 v203, v10
	v_mul_f32_e32 v10, 0x3fb17218, v10
	v_fmamk_f32 v12, v10, 0x3c088888, v186
	v_fmaak_f32 v12, v10, v12, 0x3e2aaaab
	v_add_f32_e32 v11, 1.0, v11
	v_fma_f32 v12, v10, v12, 0.5
	v_rcp_f32_e32 v11, v11
	v_fma_f32 v12, v10, v12, 1.0
	v_mul_f32_e32 v12, v10, v12
	v_fma_f32 v13, v203, v203, -1.0
	v_cmp_lt_f32_e32 vcc, s76, v10
	v_mul_f32_e32 v11, v194, v11
	v_exp_f32_e32 v210, v11
	v_cndmask_b32_e32 v10, v13, v12, vcc
	v_add_f32_e32 v12, v191, v43
	v_mul_f32_e32 v12, 0xbfb8aa3b, v12
	v_mul_f32_e32 v11, 0x3fb17218, v11
	v_exp_f32_e32 v12, v12
	v_fmamk_f32 v14, v11, 0x3c088888, v186
	v_fmaak_f32 v14, v11, v14, 0x3e2aaaab
	v_fma_f32 v14, v11, v14, 0.5
	v_fma_f32 v14, v11, v14, 1.0
	v_sqrt_f32_e64 v10, -v10
	v_add_f32_e32 v12, 1.0, v12
	v_mul_f32_e32 v14, v11, v14
	v_fma_f32 v15, v210, v210, -1.0
	v_cmp_lt_f32_e32 vcc, s76, v11
	v_rcp_f32_e32 v12, v12
	v_mul_f32_e32 v216, v10, v9
	v_cndmask_b32_e32 v11, v15, v14, vcc
	v_sqrt_f32_e64 v11, -v11
	s_waitcnt lgkmcnt(0)
	v_lshlrev_b32_e32 v9, 16, v101
	v_mul_f32_e32 v9, v12, v9
	v_add_f32_e32 v10, v192, v28
	v_mul_f32_e32 v215, v11, v9
	v_add_f32_e32 v11, v191, v44
	v_mul_f32_e32 v11, 0xbfb8aa3b, v11
	v_exp_f32_e32 v11, v11
	v_mul_f32_e32 v10, 0xbfb8aa3b, v10
	v_exp_f32_e32 v10, v10
	v_add_f32_e32 v11, 1.0, v11
	v_rcp_f32_e32 v11, v11
	v_add_f32_e32 v10, 1.0, v10
	v_rcp_f32_e32 v10, v10
	s_waitcnt lgkmcnt(0)
	v_lshlrev_b32_e32 v9, 16, v102
	v_mul_f32_e32 v9, v11, v9
	v_add_f32_e32 v11, v192, v29
	v_mul_f32_e32 v11, 0xbfb8aa3b, v11
	v_exp_f32_e32 v11, v11
	v_mul_f32_e32 v10, v194, v10
	v_exp_f32_e32 v208, v10
	v_mul_f32_e32 v10, 0x3fb17218, v10
	v_fmamk_f32 v12, v10, 0x3c088888, v186
	v_fmaak_f32 v12, v10, v12, 0x3e2aaaab
	v_add_f32_e32 v11, 1.0, v11
	v_fma_f32 v12, v10, v12, 0.5
	v_rcp_f32_e32 v11, v11
	v_fma_f32 v12, v10, v12, 1.0
	v_mul_f32_e32 v12, v10, v12
	v_fma_f32 v13, v208, v208, -1.0
	v_cmp_lt_f32_e32 vcc, s76, v10
	v_mul_f32_e32 v11, v194, v11
	v_exp_f32_e32 v218, v11
	v_cndmask_b32_e32 v10, v13, v12, vcc
	v_add_f32_e32 v12, v191, v45
	v_mul_f32_e32 v12, 0xbfb8aa3b, v12
	v_mul_f32_e32 v11, 0x3fb17218, v11
	v_exp_f32_e32 v12, v12
	v_fmamk_f32 v14, v11, 0x3c088888, v186
	v_fmaak_f32 v14, v11, v14, 0x3e2aaaab
	v_fma_f32 v14, v11, v14, 0.5
	v_fma_f32 v14, v11, v14, 1.0
	v_sqrt_f32_e64 v10, -v10
	v_add_f32_e32 v12, 1.0, v12
	v_mul_f32_e32 v14, v11, v14
	v_fma_f32 v15, v218, v218, -1.0
	v_cmp_lt_f32_e32 vcc, s76, v11
	v_rcp_f32_e32 v12, v12
	v_mul_f32_e32 v227, v10, v9
	v_cndmask_b32_e32 v11, v15, v14, vcc
	v_sqrt_f32_e64 v11, -v11
	s_waitcnt lgkmcnt(0)
	v_lshlrev_b32_e32 v9, 16, v103
	v_mul_f32_e32 v9, v12, v9
	v_add_f32_e32 v10, v192, v30
	v_mul_f32_e32 v226, v11, v9
	v_add_f32_e32 v11, v191, v46
	v_mul_f32_e32 v11, 0xbfb8aa3b, v11
	v_exp_f32_e32 v11, v11
	v_mul_f32_e32 v10, 0xbfb8aa3b, v10
	v_exp_f32_e32 v10, v10
	v_add_f32_e32 v11, 1.0, v11
	v_rcp_f32_e32 v11, v11
	v_add_f32_e32 v10, 1.0, v10
	v_rcp_f32_e32 v10, v10
	s_waitcnt lgkmcnt(0)
	v_lshlrev_b32_e32 v9, 16, v104
	v_mul_f32_e32 v9, v11, v9
	v_add_f32_e32 v11, v192, v31
	v_mul_f32_e32 v11, 0xbfb8aa3b, v11
	v_exp_f32_e32 v11, v11
	v_mul_f32_e32 v10, v194, v10
	v_exp_f32_e32 v213, v10
	v_mul_f32_e32 v10, 0x3fb17218, v10
	v_fmamk_f32 v12, v10, 0x3c088888, v186
	v_fmaak_f32 v12, v10, v12, 0x3e2aaaab
	v_add_f32_e32 v11, 1.0, v11
	v_fma_f32 v12, v10, v12, 0.5
	v_rcp_f32_e32 v11, v11
	v_fma_f32 v12, v10, v12, 1.0
	v_mul_f32_e32 v12, v10, v12
	v_fma_f32 v13, v213, v213, -1.0
	v_cmp_lt_f32_e32 vcc, s76, v10
	v_mul_f32_e32 v11, v194, v11
	v_exp_f32_e32 v220, v11
	v_cndmask_b32_e32 v10, v13, v12, vcc
	v_add_f32_e32 v12, v191, v47
	v_mul_f32_e32 v12, 0xbfb8aa3b, v12
	v_mul_f32_e32 v11, 0x3fb17218, v11
	v_exp_f32_e32 v12, v12
	v_fmamk_f32 v14, v11, 0x3c088888, v186
	v_fmaak_f32 v14, v11, v14, 0x3e2aaaab
	v_fma_f32 v14, v11, v14, 0.5
	v_fma_f32 v14, v11, v14, 1.0
	v_sqrt_f32_e64 v10, -v10
	v_add_f32_e32 v12, 1.0, v12
	v_mul_f32_e32 v14, v11, v14
	v_fma_f32 v15, v220, v220, -1.0
	v_cmp_lt_f32_e32 vcc, s76, v11
	v_rcp_f32_e32 v12, v12
	v_mul_f32_e32 v224, v10, v9
	v_cndmask_b32_e32 v11, v15, v14, vcc
	v_sqrt_f32_e64 v11, -v11
	s_waitcnt lgkmcnt(0)
; __device__ __forceinline__ float bf2f(bf16_t b) { return __uint_as_float(((unsigned)b) << 16); }
; __device__ __forceinline__ void scan_loadw(PP p, int dir, int n, int ct, int l31, int hl, ScanW& w) {
;     unsigned chv = (unsigned)(32 * ct + l31); asm volatile("" : "+v"(chv));
;     const unsigned ch = (unsigned)(dir * 512 + 64 * n) + chv;
;     w.ba = p->lru_b_a[ch]; w.bi = p->lru_b_i[ch];
;     w.sp8l2 = ((const float*)(p->ws + WS_SP8))[ch] * 1.4426950408889634f;
;     const bf16_t* wa_b = (const bf16_t*)(p->ws + WS_LRU) + (size_t)((dir * 2 + 0) * 8 + n) * 4096;
;     const bf16_t* wi_b = (const bf16_t*)(p->ws + WS_LRU) + (size_t)((dir * 2 + 1) * 8 + n) * 4096;
;     const unsigned lo = chv * 64u + 8u * (unsigned)hl;
; #pragma unroll
;     for (int st = 0; st < 4; ++st) { w.wfa[st] = *(const bf16x8*)(wa_b + lo + 16 * st); w.wfi[st] = *(const bf16x8*)(wi_b + lo + 16 * st); }
; }
; template <int DIR>
; __device__ __forceinline__ void scan_dir(PP p, const bf16_t* xs, const ScanW& w, ScanW& wn, int ndir, int nct, bool do_next, int n, int ct, int l31, int hl, int id, int rowbase, bool latent, float (&hf)[2][16]) {
;     ...
;         for (int i = 0; i < 16; ++i) {
;             const int token = 32 * rt + 8 * (i >> 2) + 4 * hl + (i & 3);
;             const float xv = bf2f(xs[token * XS + ch]);
;             const float rr = fast_sigmoid(ga[i] + ba), ii = fast_sigmoid(gi[i] + bi);
;             const float la2 = rr * sp8l2;
;             const float av = __builtin_amdgcn_exp2f(la2);
;             const float t2 = la2 * 1.3862943611f;
;             float em1p = t2 * (1.0f + t2 * (0.5f + t2 * (0.16666667f + t2 * (0.041666668f + t2 * 0.0083333333f)))), em1e = __builtin_fmaf(av, av, -1.0f);
;             asm volatile("" : "+v"(em1p), "+v"(em1e));
;             const float em1 = (t2 > -0.1f) ? em1p : em1e;
;             a[rt][i] = av; u[rt][i] = __builtin_amdgcn_sqrtf(-em1) * (ii * xv);
;         }
;     }
;     float Ao[8], Ho[8], Ap[8], Hp[8];
; #pragma unroll
;     for (int k = 0; k < 8; ++k) {
;         const int rt = k >> 2, g = k & 3;
;         float H = 0.f, A = 1.f;
; #pragma unroll
;         for (int jj = 0; jj < 4; ++jj) { const int j = DIR ? 3 - jj : jj; const float av = a[rt][4 * g + j]; H = av * H + u[rt][4 * g + j]; A *= av; }
;         Ao[k] = A; Ho[k] = H; Ap[k] = __shfl_xor(A, 32); Hp[k] = __shfl_xor(H, 32);
	v_lshlrev_b32_e32 v9, 16, v105
	v_mul_f32_e32 v9, v12, v9
	v_add_f32_e32 v10, v192, v32
	v_mul_f32_e32 v223, v11, v9
	v_add_f32_e32 v11, v191, v48
	v_mul_f32_e32 v11, 0xbfb8aa3b, v11
	v_exp_f32_e32 v11, v11
	v_mul_f32_e32 v10, 0xbfb8aa3b, v10
	v_exp_f32_e32 v10, v10
	v_add_f32_e32 v11, 1.0, v11
	v_rcp_f32_e32 v11, v11
	v_add_f32_e32 v10, 1.0, v10
	v_rcp_f32_e32 v10, v10
	s_waitcnt lgkmcnt(0)
	v_lshlrev_b32_e32 v9, 16, v106
	v_mul_f32_e32 v9, v11, v9
	v_add_f32_e32 v11, v192, v33
	v_mul_f32_e32 v11, 0xbfb8aa3b, v11
	v_exp_f32_e32 v11, v11
	v_mul_f32_e32 v10, v194, v10
	v_exp_f32_e32 v219, v10
	v_mul_f32_e32 v10, 0x3fb17218, v10
	v_fmamk_f32 v12, v10, 0x3c088888, v186
	v_fmaak_f32 v12, v10, v12, 0x3e2aaaab
	v_add_f32_e32 v11, 1.0, v11
	v_fma_f32 v12, v10, v12, 0.5
	v_rcp_f32_e32 v11, v11
	v_fma_f32 v12, v10, v12, 1.0
	v_mul_f32_e32 v12, v10, v12
	v_fma_f32 v13, v219, v219, -1.0
	v_cmp_lt_f32_e32 vcc, s76, v10
	v_mul_f32_e32 v11, v194, v11
	v_exp_f32_e32 v225, v11
	v_cndmask_b32_e32 v10, v13, v12, vcc
	v_add_f32_e32 v12, v191, v49
	v_mul_f32_e32 v12, 0xbfb8aa3b, v12
	v_mul_f32_e32 v11, 0x3fb17218, v11
	v_exp_f32_e32 v12, v12
	v_fmamk_f32 v13, v11, 0x3c088888, v186
	v_fmaak_f32 v13, v11, v13, 0x3e2aaaab
	v_fma_f32 v13, v11, v13, 0.5
	ds_read_u16 v0, v0 offset:61360
	v_fma_f32 v13, v11, v13, 1.0
	v_add_f32_e32 v12, 1.0, v12
	v_mul_f32_e32 v13, v11, v13
	v_fma_f32 v14, v225, v225, -1.0
	v_cmp_lt_f32_e32 vcc, s76, v11
	v_sqrt_f32_e64 v10, -v10
	v_rcp_f32_e32 v12, v12
	s_waitcnt lgkmcnt(0)
	v_lshlrev_b32_e32 v0, 16, v0
	v_cndmask_b32_e32 v11, v14, v13, vcc
	v_sqrt_f32_e64 v11, -v11
	v_mul_f32_e32 v229, v10, v9
	v_mul_f32_e32 v0, v12, v0
	v_and_b32_e32 v9, 64, v188
	v_mul_f32_e32 v228, v11, v0
	v_xor_b32_e32 v0, 32, v188
	v_add_u32_e32 v9, 64, v9
	v_cmp_lt_i32_e32 vcc, v0, v9
	v_fma_f32 v9, 0, v50, v2
	v_fma_f32 v9, v52, v9, v3
	v_fma_f32 v9, v51, v9, v4
	v_fma_f32 v34, v54, v9, v5
	v_fma_f32 v9, 0, v53, v6
	v_fma_f32 v9, v55, v9, v7
	v_fma_f32 v9, v67, v9, v8
	v_fma_f32 v255, v69, v9, v76
	v_fma_f32 v9, 0, v68, v74
	v_fma_f32 v9, v71, v9, v73
	v_mul_f32_e32 v10, v50, v52
	v_fma_f32 v9, v70, v9, v209
	v_mul_f32_e32 v10, v51, v10
	v_fma_f32 v251, v75, v9, v217
	v_fma_f32 v9, 0, v72, v197
	v_mul_f32_e32 v35, v54, v10
	v_mul_f32_e32 v10, v53, v55
	v_fma_f32 v9, v78, v9, v199
	v_mul_f32_e32 v10, v67, v10
	v_fma_f32 v9, v77, v9, v204
	v_mul_f32_e32 v154, v69, v10
	v_mul_f32_e32 v10, v68, v71
	v_fma_f32 v247, v79, v9, v202
	v_fma_f32 v9, 0, v80, v196
	v_mul_f32_e32 v10, v70, v10
	v_fma_f32 v9, v146, v9, v195
	v_mul_f32_e32 v253, v75, v10
	v_mul_f32_e32 v10, v72, v78
	v_fma_f32 v9, v81, v9, v214
	v_mul_f32_e32 v10, v77, v10
	v_fma_f32 v243, v198, v9, v211
	v_fma_f32 v9, 0, v147, v206
	v_mul_f32_e32 v249, v79, v10
	v_mul_f32_e32 v10, v80, v146
	v_fma_f32 v9, v201, v9, v205
	v_mul_f32_e32 v10, v81, v10
	v_fma_f32 v9, v200, v9, v222
	v_mul_f32_e32 v245, v198, v10
	v_mul_f32_e32 v10, v147, v201
	v_fma_f32 v239, v207, v9, v221
	v_fma_f32 v9, 0, v203, v216
	v_mul_f32_e32 v10, v200, v10
	v_fma_f32 v9, v210, v9, v215
	v_mul_f32_e32 v241, v207, v10
	v_mul_f32_e32 v10, v203, v210
	v_fma_f32 v9, v208, v9, v227
	v_mul_f32_e32 v10, v208, v10
	v_fma_f32 v234, v218, v9, v226
	v_fma_f32 v9, 0, v213, v224
	v_mul_f32_e32 v236, v218, v10
	v_fma_f32 v9, v220, v9, v223
	v_mul_f32_e32 v10, v213, v220
	v_cndmask_b32_e32 v0, v188, v0, vcc
	v_fma_f32 v9, v219, v9, v229
	v_mul_f32_e32 v10, v219, v10
	v_lshlrev_b32_e32 v0, 2, v0
	v_fma_f32 v230, v225, v9, v228
	v_mul_f32_e32 v231, v225, v10
	ds_bpermute_b32 v36, v0, v35
	ds_bpermute_b32 v37, v0, v34
	ds_bpermute_b32 v155, v0, v154
	ds_bpermute_b32 v212, v0, v255
	ds_bpermute_b32 v254, v0, v253
	ds_bpermute_b32 v252, v0, v251
	ds_bpermute_b32 v250, v0, v249
	ds_bpermute_b32 v248, v0, v247
	ds_bpermute_b32 v246, v0, v245
	ds_bpermute_b32 v244, v0, v243
	ds_bpermute_b32 v242, v0, v241
	ds_bpermute_b32 v240, v0, v239
	ds_bpermute_b32 v237, v0, v236
	ds_bpermute_b32 v235, v0, v234
	ds_bpermute_b32 v232, v0, v231
	ds_bpermute_b32 v233, v0, v230
	v_cndmask_b32_e64 v0, 0, 1, s[22:23]
	v_cmp_ne_u32_e64 s[4:5], 1, v0
	s_andn2_b64 vcc, exec, s[22:23]
	s_cbranch_vccnz .LBB0_380
	v_or_b32_e32 v9, s48, v148
	s_load_dwordx2 s[48:49], s[8:9], 0x58
	s_load_dwordx2 s[82:83], s[8:9], 0x68
	v_add_u32_e32 v0, s50, v9
	v_lshlrev_b64 v[10:11], 2, v[0:1]
	v_lshl_or_b32 v0, v9, 6, v149
	s_waitcnt lgkmcnt(0)
	v_lshl_add_u64 v[12:13], s[48:49], 0, v[10:11]
	global_load_dword v189, v[12:13], off
	v_lshl_add_u64 v[12:13], s[82:83], 0, v[10:11]
	global_load_dword v190, v[12:13], off
	v_lshl_add_u64 v[10:11], s[12:13], 0, v[10:11]
	v_lshlrev_b64 v[12:13], 1, v[0:1]
	v_lshl_add_u64 v[14:15], s[20:21], 0, v[12:13]
	v_lshl_add_u64 v[12:13], s[16:17], 0, v[12:13]
	global_load_dword v0, v[10:11], off
	global_load_dwordx4 v[82:85], v[14:15], off
	global_load_dwordx4 v[86:89], v[14:15], off offset:32
	global_load_dwordx4 v[90:93], v[14:15], off offset:64
	global_load_dwordx4 v[94:97], v[12:13], off offset:32
	global_load_dwordx4 v[102:105], v[12:13], off offset:64
	global_load_dwordx4 v[98:101], v[12:13], off
	global_load_dwordx4 v[106:109], v[14:15], off offset:96
	global_load_dwordx4 v[110:113], v[12:13], off offset:96
	s_waitcnt vmcnt(8)
	v_mul_f32_e32 v193, 0x3fb8aa3b, v0

; __device__ __forceinline__ float bf2f(bf16_t b) { return __uint_as_float(((unsigned)b) << 16); }
; __device__ __forceinline__ float fast_sigmoid(float x) { return __builtin_amdgcn_rcpf(1.0f + __builtin_amdgcn_exp2f(-1.4426950408889634f * x)); }
; template <int DIR>
; __device__ __forceinline__ void scan_dir(PP p, const bf16_t* xs, const ScanW& w, ScanW& wn, int ndir, int nct, bool do_next, int n, int ct, int l31, int hl, int id, int rowbase, bool latent, float (&hf)[2][16]) {
;     ...
;     for (int rt = 0; rt < 2; ++rt) {
;         bf16x8 af[4];
; #pragma unroll
;         for (int st = 0; st < 4; ++st) af[st] = *(const bf16x8*)(xs + (32 * rt + l31) * XS + 64 * n + 16 * st + 8 * hl);
;         f32x16 ga, gi;
; #pragma unroll
;         for (int i = 0; i < 16; ++i) { ga[i] = 0.f; gi[i] = 0.f; }
; #pragma unroll
;         for (int st = 0; st < 4; ++st) { ga = __builtin_amdgcn_mfma_f32_32x32x16_bf16(af[st], wfa[st], ga, 0, 0, 0); gi = __builtin_amdgcn_mfma_f32_32x32x16_bf16(af[st], wfi[st], gi, 0, 0, 0); }
; #pragma unroll
;         for (int i = 0; i < 16; ++i) {
;             const int token = 32 * rt + 8 * (i >> 2) + 4 * hl + (i & 3);
;             const float xv = bf2f(xs[token * XS + ch]);
;             const float rr = fast_sigmoid(ga[i] + ba), ii = fast_sigmoid(gi[i] + bi);
;             const float la2 = rr * sp8l2;
;             const float av = __builtin_amdgcn_exp2f(la2);
;             const float t2 = la2 * 1.3862943611f;
;             float em1p = t2 * (1.0f + t2 * (0.5f + t2 * (0.16666667f + t2 * (0.041666668f + t2 * 0.0083333333f)))), em1e = __builtin_fmaf(av, av, -1.0f);
;             asm volatile("" : "+v"(em1p), "+v"(em1e));
;             const float em1 = (t2 > -0.1f) ? em1p : em1e;
;             a[rt][i] = av; u[rt][i] = __builtin_amdgcn_sqrtf(-em1) * (ii * xv);
;         }
.LBB0_445:
	ds_read_b128 v[34:37], v187
	v_lshl_or_b32 v146, s80, 5, v150
	v_lshl_add_u32 v74, v146, 1, 0
	v_add_u32_e32 v0, v74, v151
	ds_read_u16 v75, v0
	ds_read_b128 v[66:69], v187 offset:32
	ds_read_b128 v[70:73], v187 offset:64
	v_add_u32_e32 v213, v74, v152
	s_and_b64 s[4:5], s[22:23], s[44:45]
	s_waitcnt vmcnt(7) lgkmcnt(3)
	v_mfma_f32_32x32x16_bf16 v[50:65], v[34:37], v[82:85], 0
	s_waitcnt vmcnt(2)
	v_mfma_f32_32x32x16_bf16 v[34:49], v[34:37], v[98:101], 0
	s_waitcnt lgkmcnt(1)
	v_mfma_f32_32x32x16_bf16 v[50:65], v[66:69], v[86:89], v[50:65]
	v_mfma_f32_32x32x16_bf16 v[34:49], v[66:69], v[94:97], v[34:49]
	ds_read_b128 v[66:69], v187 offset:96
	s_waitcnt lgkmcnt(1)
	v_mfma_f32_32x32x16_bf16 v[50:65], v[70:73], v[90:93], v[50:65]
	v_mfma_f32_32x32x16_bf16 v[34:49], v[70:73], v[102:105], v[34:49]
	s_waitcnt vmcnt(1) lgkmcnt(0)
	v_add_u32_e32 v145, v74, v185
	ds_read_u16 v114, v145
	ds_read_u16 v115, v145 offset:1040
	ds_read_u16 v116, v145 offset:2080
	ds_read_u16 v117, v213
	ds_read_u16 v118, v213 offset:1040
	ds_read_u16 v119, v213 offset:2080
	ds_read_u16 v120, v213 offset:3120
	ds_read_u16 v121, v213 offset:8320
	ds_read_u16 v122, v213 offset:9360
	ds_read_u16 v123, v213 offset:10400
	ds_read_u16 v124, v213 offset:24960
	ds_read_u16 v125, v213 offset:26000
	ds_read_u16 v126, v213 offset:27040
	ds_read_u16 v127, v213 offset:28080
	ds_read_u16 v128, v0 offset:41600
	ds_read_u16 v129, v0 offset:42640
	ds_read_u16 v130, v0 offset:43680
	ds_read_u16 v131, v0 offset:44720
	ds_read_u16 v132, v0 offset:49920
	ds_read_u16 v133, v0 offset:50960
	ds_read_u16 v134, v0 offset:52000
	ds_read_u16 v135, v0 offset:53040
	ds_read_u16 v136, v0 offset:58240
	ds_read_u16 v137, v0 offset:59280
	ds_read_u16 v138, v0 offset:60320
	v_mfma_f32_32x32x16_bf16 v[50:65], v[66:69], v[106:109], v[50:65]
	s_waitcnt vmcnt(0)
	v_mfma_f32_32x32x16_bf16 v[34:49], v[66:69], v[110:113], v[34:49]
	s_nop 9
	v_add_f32_e32 v50, v189, v50
	v_mul_f32_e32 v50, 0xbfb8aa3b, v50
	v_exp_f32_e32 v50, v50
	v_add_f32_e32 v51, v189, v51
	v_mul_f32_e32 v51, 0xbfb8aa3b, v51
	v_exp_f32_e32 v51, v51
	v_add_f32_e32 v50, 1.0, v50
	v_add_f32_e32 v34, v190, v34
	v_mul_f32_e32 v34, 0xbfb8aa3b, v34
	v_exp_f32_e32 v34, v34
	v_rcp_f32_e32 v50, v50
	v_add_f32_e32 v35, v190, v35
	v_mul_f32_e32 v35, 0xbfb8aa3b, v35
	v_add_f32_e32 v34, 1.0, v34
	v_mul_f32_e32 v50, v193, v50
	v_rcp_f32_e32 v67, v34
	v_exp_f32_e32 v34, v50
	v_mul_f32_e32 v50, 0x3fb17218, v50
	v_fmamk_f32 v68, v50, 0x3c088888, v186
	v_fmaak_f32 v68, v50, v68, 0x3e2aaaab
	v_exp_f32_e32 v35, v35
	v_add_f32_e32 v51, 1.0, v51
	v_fma_f32 v68, v50, v68, 0.5
	v_rcp_f32_e32 v51, v51
	v_fma_f32 v68, v50, v68, 1.0
	v_mul_f32_e32 v68, v50, v68
	v_fma_f32 v69, v34, v34, -1.0
	v_cmp_lt_f32_e32 vcc, s76, v50
	v_add_f32_e32 v35, 1.0, v35
	v_lshlrev_b32_e32 v66, 16, v75
	v_cndmask_b32_e32 v50, v69, v68, vcc
	v_rcp_f32_e32 v69, v35
	v_mul_f32_e32 v35, v193, v51
	v_exp_f32_e32 v147, v35
	v_mul_f32_e32 v35, 0x3fb17218, v35
	v_fmamk_f32 v51, v35, 0x3c088888, v186
	v_fmaak_f32 v51, v35, v51, 0x3e2aaaab
	v_mul_f32_e32 v66, v67, v66
	v_add_u32_e32 v67, v74, v185
	v_fma_f32 v51, v35, v51, 0.5
	v_fma_f32 v51, v35, v51, 1.0
	v_sqrt_f32_e64 v50, -v50
	v_mul_f32_e32 v51, v35, v51
	v_fma_f32 v70, v147, v147, -1.0
	v_cmp_lt_f32_e32 vcc, s76, v35
	v_add_f32_e32 v36, v190, v36
	v_mul_f32_e32 v36, 0xbfb8aa3b, v36
	v_cndmask_b32_e32 v35, v70, v51, vcc
	v_sqrt_f32_e64 v51, -v35
	v_exp_f32_e32 v36, v36
	v_mul_f32_e32 v35, v66, v50
	s_waitcnt lgkmcnt(0)
	v_lshlrev_b32_e32 v50, 16, v114
	v_mul_f32_e32 v50, v69, v50
	v_mul_f32_e32 v195, v50, v51
	v_add_f32_e32 v36, 1.0, v36
	v_rcp_f32_e32 v36, v36
	v_add_f32_e32 v51, v189, v52
	v_mul_f32_e32 v51, 0xbfb8aa3b, v51
	v_exp_f32_e32 v51, v51
	s_waitcnt lgkmcnt(0)
	v_lshlrev_b32_e32 v50, 16, v115
	v_mul_f32_e32 v36, v36, v50
	v_add_f32_e32 v50, v189, v53
	v_mul_f32_e32 v50, 0xbfb8aa3b, v50
	v_exp_f32_e32 v50, v50
	v_add_f32_e32 v51, 1.0, v51
	v_rcp_f32_e32 v51, v51
	v_add_f32_e32 v37, v190, v37
	v_add_f32_e32 v50, 1.0, v50
	v_rcp_f32_e32 v50, v50
	v_mul_f32_e32 v51, v193, v51
	v_exp_f32_e32 v196, v51
	v_mul_f32_e32 v51, 0x3fb17218, v51
	v_fmamk_f32 v52, v51, 0x3c088888, v186
	v_fmaak_f32 v52, v51, v52, 0x3e2aaaab
	v_mul_f32_e32 v50, v193, v50
	v_fma_f32 v52, v51, v52, 0.5
	v_mul_f32_e32 v37, 0xbfb8aa3b, v37
	v_exp_f32_e32 v198, v50
	v_mul_f32_e32 v50, 0x3fb17218, v50
	v_fma_f32 v52, v51, v52, 1.0
	v_exp_f32_e32 v37, v37
	v_fmamk_f32 v53, v50, 0x3c088888, v186
	v_mul_f32_e32 v52, v51, v52
	v_fma_f32 v66, v196, v196, -1.0
	v_fmaak_f32 v53, v50, v53, 0x3e2aaaab
	v_cmp_lt_f32_e32 vcc, s76, v51
	v_fma_f32 v53, v50, v53, 0.5
	v_fma_f32 v53, v50, v53, 1.0
	v_cndmask_b32_e32 v51, v66, v52, vcc
	v_sqrt_f32_e64 v51, -v51
	v_add_f32_e32 v37, 1.0, v37
	v_mul_f32_e32 v53, v50, v53
	v_fma_f32 v66, v198, v198, -1.0
	v_cmp_lt_f32_e32 vcc, s76, v50
	v_rcp_f32_e32 v37, v37
	v_mul_f32_e32 v197, v36, v51
	v_cndmask_b32_e32 v50, v66, v53, vcc
	v_sqrt_f32_e64 v50, -v50
	s_waitcnt lgkmcnt(0)
	v_lshlrev_b32_e32 v36, 16, v116
	v_mul_f32_e32 v36, v37, v36
	v_add_f32_e32 v38, v190, v38
	v_mul_f32_e32 v199, v50, v36
	v_mul_f32_e32 v38, 0xbfb8aa3b, v38
	v_exp_f32_e32 v38, v38
	v_add_f32_e32 v37, v189, v54
	v_mul_f32_e32 v37, 0xbfb8aa3b, v37
	v_exp_f32_e32 v37, v37
	s_waitcnt lgkmcnt(0)
; __device__ __forceinline__ float bf2f(bf16_t b) { return __uint_as_float(((unsigned)b) << 16); }
; __device__ __forceinline__ float fast_sigmoid(float x) { return __builtin_amdgcn_rcpf(1.0f + __builtin_amdgcn_exp2f(-1.4426950408889634f * x)); }
; template <int DIR>
; __device__ __forceinline__ void scan_dir(PP p, const bf16_t* xs, const ScanW& w, ScanW& wn, int ndir, int nct, bool do_next, int n, int ct, int l31, int hl, int id, int rowbase, bool latent, float (&hf)[2][16]) {
;     ...
;         for (int i = 0; i < 16; ++i) {
;             const int token = 32 * rt + 8 * (i >> 2) + 4 * hl + (i & 3);
;             const float xv = bf2f(xs[token * XS + ch]);
;             const float rr = fast_sigmoid(ga[i] + ba), ii = fast_sigmoid(gi[i] + bi);
;             const float la2 = rr * sp8l2;
;             const float av = __builtin_amdgcn_exp2f(la2);
;             const float t2 = la2 * 1.3862943611f;
;             float em1p = t2 * (1.0f + t2 * (0.5f + t2 * (0.16666667f + t2 * (0.041666668f + t2 * 0.0083333333f)))), em1e = __builtin_fmaf(av, av, -1.0f);
;             asm volatile("" : "+v"(em1p), "+v"(em1e));
;             const float em1 = (t2 > -0.1f) ? em1p : em1e;
;             a[rt][i] = av; u[rt][i] = __builtin_amdgcn_sqrtf(-em1) * (ii * xv);
;         }
	v_lshlrev_b32_e32 v50, 16, v117
	v_add_f32_e32 v36, 1.0, v38
	v_rcp_f32_e32 v38, v36
	v_add_f32_e32 v37, 1.0, v37
	v_rcp_f32_e32 v37, v37
	v_add_f32_e32 v39, v190, v39
	v_mul_f32_e32 v50, v38, v50
	v_add_f32_e32 v38, v189, v55
	v_mul_f32_e32 v38, 0xbfb8aa3b, v38
	v_exp_f32_e32 v38, v38
	v_mul_f32_e32 v37, v193, v37
	v_exp_f32_e32 v36, v37
	v_mul_f32_e32 v37, 0x3fb17218, v37
	v_fmamk_f32 v51, v37, 0x3c088888, v186
	v_fmaak_f32 v51, v37, v51, 0x3e2aaaab
	v_add_f32_e32 v38, 1.0, v38
	v_fma_f32 v51, v37, v51, 0.5
	v_rcp_f32_e32 v38, v38
	v_fma_f32 v51, v37, v51, 1.0
	v_mul_f32_e32 v39, 0xbfb8aa3b, v39
	v_mul_f32_e32 v51, v37, v51
	v_fma_f32 v52, v36, v36, -1.0
	v_exp_f32_e32 v39, v39
	v_cmp_lt_f32_e32 vcc, s76, v37
	v_add_f32_e32 v40, v190, v40
	v_add_f32_e32 v39, 1.0, v39
	v_cndmask_b32_e32 v37, v52, v51, vcc
	v_mul_f32_e32 v52, v193, v38
	v_exp_f32_e32 v38, v52
	v_mul_f32_e32 v52, 0x3fb17218, v52
	v_sqrt_f32_e64 v37, -v37
	v_fmamk_f32 v53, v52, 0x3c088888, v186
	v_rcp_f32_e32 v39, v39
	v_fmaak_f32 v53, v52, v53, 0x3e2aaaab
	v_mul_f32_e32 v40, 0xbfb8aa3b, v40
	v_fma_f32 v53, v52, v53, 0.5
	v_exp_f32_e32 v40, v40
	v_fma_f32 v53, v52, v53, 1.0
	v_mul_f32_e32 v53, v52, v53
	v_fma_f32 v54, v38, v38, -1.0
	v_mul_f32_e32 v37, v37, v50
	s_waitcnt lgkmcnt(0)
	v_lshlrev_b32_e32 v50, 16, v118
	v_mul_f32_e32 v39, v39, v50
	v_add_f32_e32 v51, v189, v56
	v_mul_f32_e32 v51, 0xbfb8aa3b, v51
	v_add_f32_e32 v40, 1.0, v40
	v_exp_f32_e32 v51, v51
	v_rcp_f32_e32 v40, v40
	s_waitcnt lgkmcnt(0)
	v_lshlrev_b32_e32 v50, 16, v119
	v_cmp_lt_f32_e32 vcc, s76, v52
	v_add_f32_e32 v51, 1.0, v51
	v_mul_f32_e32 v40, v40, v50
	v_add_f32_e32 v50, v189, v57
	v_rcp_f32_e32 v51, v51
	v_mul_f32_e32 v50, 0xbfb8aa3b, v50
	v_cndmask_b32_e32 v52, v54, v53, vcc
	v_exp_f32_e32 v50, v50
	v_sqrt_f32_e64 v52, -v52
	v_mul_f32_e32 v51, v193, v51
	v_exp_f32_e32 v200, v51
	v_mul_f32_e32 v51, 0x3fb17218, v51
	v_add_f32_e32 v50, 1.0, v50
	v_mul_f32_e32 v39, v52, v39
	v_fmamk_f32 v52, v51, 0x3c088888, v186
	v_rcp_f32_e32 v50, v50
	v_fmaak_f32 v52, v51, v52, 0x3e2aaaab
	v_add_f32_e32 v41, v190, v41
	v_fma_f32 v52, v51, v52, 0.5
	v_mul_f32_e32 v41, 0xbfb8aa3b, v41
	v_fma_f32 v52, v51, v52, 1.0
	v_exp_f32_e32 v41, v41
	v_mul_f32_e32 v52, v51, v52
	v_fma_f32 v53, v200, v200, -1.0
	v_mul_f32_e32 v50, v193, v50
	v_cmp_lt_f32_e32 vcc, s76, v51
	v_exp_f32_e32 v202, v50
	v_mul_f32_e32 v50, 0x3fb17218, v50
	v_cndmask_b32_e32 v51, v53, v52, vcc
	v_fmamk_f32 v53, v50, 0x3c088888, v186
	v_sqrt_f32_e64 v51, -v51
	v_add_f32_e32 v41, 1.0, v41
	v_fmaak_f32 v53, v50, v53, 0x3e2aaaab
	v_rcp_f32_e32 v41, v41
	v_fma_f32 v53, v50, v53, 0.5
	v_fma_f32 v53, v50, v53, 1.0
	v_mul_f32_e32 v53, v50, v53
	v_fma_f32 v54, v202, v202, -1.0
	v_cmp_lt_f32_e32 vcc, s76, v50
	v_mul_f32_e32 v201, v51, v40
	s_waitcnt lgkmcnt(0)
	v_lshlrev_b32_e32 v40, 16, v120
	v_cndmask_b32_e32 v50, v54, v53, vcc
	v_sqrt_f32_e64 v50, -v50
	v_mul_f32_e32 v40, v41, v40
	v_add_f32_e32 v41, v189, v58
	v_mul_f32_e32 v41, 0xbfb8aa3b, v41
	v_exp_f32_e32 v41, v41
	v_add_f32_e32 v42, v190, v42
	v_mul_f32_e32 v203, v50, v40
	v_mul_f32_e32 v42, 0xbfb8aa3b, v42
	v_exp_f32_e32 v42, v42
	v_add_f32_e32 v41, 1.0, v41
	v_rcp_f32_e32 v41, v41
	s_waitcnt lgkmcnt(0)
	v_lshlrev_b32_e32 v50, 16, v121
	v_add_f32_e32 v40, 1.0, v42
	v_rcp_f32_e32 v42, v40
	v_mul_f32_e32 v41, v193, v41
	v_exp_f32_e32 v40, v41
	v_mul_f32_e32 v41, 0x3fb17218, v41
	v_fmamk_f32 v51, v41, 0x3c088888, v186
	v_fmaak_f32 v51, v41, v51, 0x3e2aaaab
	v_mul_f32_e32 v50, v42, v50
	v_add_f32_e32 v42, v189, v59
	v_fma_f32 v51, v41, v51, 0.5
	v_mul_f32_e32 v42, 0xbfb8aa3b, v42
	v_fma_f32 v51, v41, v51, 1.0
	v_exp_f32_e32 v42, v42
	v_mul_f32_e32 v51, v41, v51
	v_fma_f32 v52, v40, v40, -1.0
	v_cmp_lt_f32_e32 vcc, s76, v41
	v_add_f32_e32 v42, 1.0, v42
	v_rcp_f32_e32 v42, v42
	v_cndmask_b32_e32 v41, v52, v51, vcc
	v_sqrt_f32_e64 v41, -v41
	v_add_f32_e32 v43, v190, v43
	v_mul_f32_e32 v52, v193, v42
	v_mul_f32_e32 v43, 0xbfb8aa3b, v43
	v_mul_f32_e32 v41, v41, v50
	s_waitcnt lgkmcnt(0)
	v_lshlrev_b32_e32 v50, 16, v122
	v_add_f32_e32 v51, v189, v60
	v_mul_f32_e32 v51, 0xbfb8aa3b, v51
	v_exp_f32_e32 v42, v52
	v_mul_f32_e32 v52, 0x3fb17218, v52
	v_exp_f32_e32 v51, v51
	v_exp_f32_e32 v43, v43
	v_fmamk_f32 v53, v52, 0x3c088888, v186
	v_fmaak_f32 v53, v52, v53, 0x3e2aaaab
	v_fma_f32 v53, v52, v53, 0.5
	v_fma_f32 v53, v52, v53, 1.0
	v_add_f32_e32 v51, 1.0, v51
	v_add_f32_e32 v43, 1.0, v43
	v_mul_f32_e32 v53, v52, v53
	v_fma_f32 v54, v42, v42, -1.0
	v_cmp_lt_f32_e32 vcc, s76, v52
	v_rcp_f32_e32 v51, v51
	v_rcp_f32_e32 v43, v43
	v_add_f32_e32 v44, v190, v44
	v_cndmask_b32_e32 v52, v54, v53, vcc
	v_sqrt_f32_e64 v52, -v52
	v_mul_f32_e32 v51, v193, v51
	v_mul_f32_e32 v43, v43, v50
	v_exp_f32_e32 v204, v51
	v_mul_f32_e32 v51, 0x3fb17218, v51
	v_mul_f32_e32 v43, v52, v43
	v_fmamk_f32 v52, v51, 0x3c088888, v186
	v_fmaak_f32 v52, v51, v52, 0x3e2aaaab
	v_mul_f32_e32 v44, 0xbfb8aa3b, v44
	v_fma_f32 v52, v51, v52, 0.5
	v_exp_f32_e32 v44, v44
	v_fma_f32 v52, v51, v52, 1.0
	v_mul_f32_e32 v52, v51, v52
	v_fma_f32 v53, v204, v204, -1.0
	v_cmp_lt_f32_e32 vcc, s76, v51
	v_add_f32_e32 v44, 1.0, v44
	v_rcp_f32_e32 v44, v44
	v_cndmask_b32_e32 v51, v53, v52, vcc
	v_add_f32_e32 v52, v189, v61
	v_mul_f32_e32 v52, 0xbfb8aa3b, v52
	v_exp_f32_e32 v52, v52
	s_waitcnt lgkmcnt(0)
; __device__ __forceinline__ float bf2f(bf16_t b) { return __uint_as_float(((unsigned)b) << 16); }
; __device__ __forceinline__ float fast_sigmoid(float x) { return __builtin_amdgcn_rcpf(1.0f + __builtin_amdgcn_exp2f(-1.4426950408889634f * x)); }
; template <int DIR>
; __device__ __forceinline__ void scan_dir(PP p, const bf16_t* xs, const ScanW& w, ScanW& wn, int ndir, int nct, bool do_next, int n, int ct, int l31, int hl, int id, int rowbase, bool latent, float (&hf)[2][16]) {
;     ...
;     for (int rt = 0; rt < 2; ++rt) {
;         bf16x8 af[4];
; #pragma unroll
;         for (int st = 0; st < 4; ++st) af[st] = *(const bf16x8*)(xs + (32 * rt + l31) * XS + 64 * n + 16 * st + 8 * hl);
;         f32x16 ga, gi;
; #pragma unroll
;         for (int i = 0; i < 16; ++i) { ga[i] = 0.f; gi[i] = 0.f; }
; #pragma unroll
;         for (int st = 0; st < 4; ++st) { ga = __builtin_amdgcn_mfma_f32_32x32x16_bf16(af[st], wfa[st], ga, 0, 0, 0); gi = __builtin_amdgcn_mfma_f32_32x32x16_bf16(af[st], wfi[st], gi, 0, 0, 0); }
; #pragma unroll
;         for (int i = 0; i < 16; ++i) {
;             const int token = 32 * rt + 8 * (i >> 2) + 4 * hl + (i & 3);
;             const float xv = bf2f(xs[token * XS + ch]);
;             const float rr = fast_sigmoid(ga[i] + ba), ii = fast_sigmoid(gi[i] + bi);
;             const float la2 = rr * sp8l2;
;             const float av = __builtin_amdgcn_exp2f(la2);
;             const float t2 = la2 * 1.3862943611f;
;             float em1p = t2 * (1.0f + t2 * (0.5f + t2 * (0.16666667f + t2 * (0.041666668f + t2 * 0.0083333333f)))), em1e = __builtin_fmaf(av, av, -1.0f);
;             asm volatile("" : "+v"(em1p), "+v"(em1e));
;             const float em1 = (t2 > -0.1f) ? em1p : em1e;
;             a[rt][i] = av; u[rt][i] = __builtin_amdgcn_sqrtf(-em1) * (ii * xv);
;         }
	v_lshlrev_b32_e32 v50, 16, v123
	v_mul_f32_e32 v50, v44, v50
	v_add_f32_e32 v45, v190, v45
	v_add_f32_e32 v44, 1.0, v52
	v_rcp_f32_e32 v44, v44
	v_mul_f32_e32 v45, 0xbfb8aa3b, v45
	v_exp_f32_e32 v52, v45
	v_add_f32_e32 v45, v189, v62
	v_mul_f32_e32 v44, v193, v44
	v_mul_f32_e32 v54, 0x3fb17218, v44
	v_mul_f32_e32 v45, 0xbfb8aa3b, v45
	v_exp_f32_e32 v205, v44
	v_fmamk_f32 v44, v54, 0x3c088888, v186
	v_exp_f32_e32 v45, v45
	v_fmaak_f32 v44, v54, v44, 0x3e2aaaab
	v_fma_f32 v44, v54, v44, 0.5
	v_fma_f32 v44, v54, v44, 1.0
	v_mul_f32_e32 v55, v54, v44
	v_add_f32_e32 v44, 1.0, v45
	v_rcp_f32_e32 v44, v44
	v_add_f32_e32 v57, v189, v63
	v_mul_f32_e32 v57, 0xbfb8aa3b, v57
	v_exp_f32_e32 v57, v57
	v_mul_f32_e32 v45, v193, v44
	v_mul_f32_e32 v154, 0x3fb17218, v45
	v_exp_f32_e32 v44, v45
	v_fmamk_f32 v45, v154, 0x3c088888, v186
	v_fmaak_f32 v45, v154, v45, 0x3e2aaaab
	v_fma_f32 v45, v154, v45, 0.5
	v_fma_f32 v45, v154, v45, 1.0
	v_mul_f32_e32 v155, v154, v45
	v_add_f32_e32 v45, 1.0, v57
	v_rcp_f32_e32 v45, v45
	v_add_f32_e32 v58, v189, v64
	v_mul_f32_e32 v58, 0xbfb8aa3b, v58
	v_exp_f32_e32 v58, v58
	v_mul_f32_e32 v57, v193, v45
	v_mul_f32_e32 v159, 0x3fb17218, v57
	v_exp_f32_e32 v45, v57
	v_fmamk_f32 v57, v159, 0x3c088888, v186
	v_fmaak_f32 v57, v159, v57, 0x3e2aaaab
	v_fma_f32 v57, v159, v57, 0.5
	v_fma_f32 v57, v159, v57, 1.0
	v_mul_f32_e32 v209, v159, v57
	v_add_f32_e32 v57, 1.0, v58
	v_rcp_f32_e32 v57, v57
	v_add_f32_e32 v58, v189, v65
	v_mul_f32_e32 v58, 0xbfb8aa3b, v58
	v_exp_f32_e32 v58, v58
	v_mul_f32_e32 v57, v193, v57
	v_mul_f32_e32 v222, 0x3fb17218, v57
	v_exp_f32_e32 v206, v57
	v_fmamk_f32 v57, v222, 0x3c088888, v186
	v_fmaak_f32 v57, v222, v57, 0x3e2aaaab
	v_fma_f32 v57, v222, v57, 0.5
	v_fma_f32 v57, v222, v57, 1.0
	v_mul_f32_e32 v223, v222, v57
	v_add_f32_e32 v57, 1.0, v58
	v_rcp_f32_e32 v57, v57
	v_sqrt_f32_e64 v51, -v51
	v_fma_f32 v56, v205, v205, -1.0
	v_fma_f32 v156, v44, v44, -1.0
	v_mul_f32_e32 v57, v193, v57
	v_mul_f32_e32 v226, 0x3fb17218, v57
	v_exp_f32_e32 v207, v57
	v_fmamk_f32 v57, v226, 0x3c088888, v186
	v_fmaak_f32 v57, v226, v57, 0x3e2aaaab
	v_fma_f32 v57, v226, v57, 0.5
	v_fma_f32 v57, v226, v57, 1.0
	v_fma_f32 v210, v45, v45, -1.0
	v_fma_f32 v224, v206, v206, -1.0
	v_mul_f32_e32 v227, v226, v57
	v_fma_f32 v228, v207, v207, -1.0
	ds_read_u16 v53, v213 offset:11440
	ds_read_u16 v70, v213 offset:16640
	ds_read_u16 v158, v213 offset:17680
	ds_read_u16 v212, v213 offset:18720
	ds_read_u16 v225, v213 offset:19760
	ds_read_b128 v[66:69], v187 offset:33280
	ds_read_b128 v[214:217], v187 offset:33312
	v_mul_f32_e32 v208, v51, v50
	v_add_f32_e32 v50, 1.0, v52
	v_cmp_lt_f32_e32 vcc, s76, v54
	v_rcp_f32_e32 v72, v50
	s_waitcnt lgkmcnt(6)
	v_lshlrev_b32_e32 v71, 16, v53
	v_cndmask_b32_e32 v50, v56, v55, vcc
	v_sqrt_f32_e64 v73, -v50
	v_mul_f32_e32 v71, v72, v71
	s_waitcnt lgkmcnt(1)
	v_mfma_f32_32x32x16_bf16 v[50:65], v[66:69], v[82:85], 0
	v_lshlrev_b32_e32 v230, 16, v70
	v_mul_f32_e32 v211, v73, v71
	v_add_f32_e32 v46, v190, v46
	v_mul_f32_e32 v46, 0xbfb8aa3b, v46
	v_exp_f32_e32 v46, v46
	ds_read_b128 v[218:221], v187 offset:33344
	v_cmp_lt_f32_e32 vcc, s76, v154
	v_mfma_f32_32x32x16_bf16 v[66:81], v[66:69], v[98:101], 0
	v_add_f32_e32 v46, 1.0, v46
	v_add_f32_e32 v47, v190, v47
	v_rcp_f32_e32 v46, v46
	v_cndmask_b32_e32 v154, v156, v155, vcc
	v_mul_f32_e32 v47, 0xbfb8aa3b, v47
	v_sqrt_f32_e64 v154, -v154
	v_exp_f32_e32 v155, v47
	s_waitcnt lgkmcnt(1)
	v_mfma_f32_32x32x16_bf16 v[66:81], v[214:217], v[94:97], v[66:81]
	v_mul_f32_e32 v46, v46, v230
	v_mul_f32_e32 v47, v154, v46
	v_add_f32_e32 v154, 1.0, v155
	v_rcp_f32_e32 v154, v154
	v_add_f32_e32 v48, v190, v48
	v_lshlrev_b32_e32 v46, 16, v158
	v_cmp_lt_f32_e32 vcc, s76, v159
	v_mfma_f32_32x32x16_bf16 v[50:65], v[214:217], v[86:89], v[50:65]
	ds_read_b128 v[214:217], v187 offset:33376
	v_mul_f32_e32 v48, 0xbfb8aa3b, v48
	v_cndmask_b32_e32 v155, v210, v209, vcc
	v_mul_f32_e32 v46, v154, v46
	v_exp_f32_e32 v154, v48
	v_add_f32_e32 v49, v190, v49
	v_sqrt_f32_e64 v155, -v155
	s_waitcnt lgkmcnt(1)
	v_mfma_f32_32x32x16_bf16 v[66:81], v[218:221], v[102:105], v[66:81]
	v_mul_f32_e32 v49, 0xbfb8aa3b, v49
	v_exp_f32_e32 v49, v49
	v_add_f32_e32 v154, 1.0, v154
	v_cmp_lt_f32_e32 vcc, s76, v222
	v_mul_f32_e32 v48, v155, v46
	v_rcp_f32_e32 v154, v154
	v_cndmask_b32_e32 v155, v224, v223, vcc
	v_mfma_f32_32x32x16_bf16 v[50:65], v[218:221], v[90:93], v[50:65]
	v_sqrt_f32_e64 v155, -v155
	v_add_f32_e32 v49, 1.0, v49
	v_rcp_f32_e32 v49, v49
	v_lshlrev_b32_e32 v46, 16, v212
	v_cmp_lt_f32_e32 vcc, s76, v226
	v_mul_f32_e32 v46, v154, v46
	v_mul_f32_e32 v209, v155, v46
	s_waitcnt lgkmcnt(0)
	v_mfma_f32_32x32x16_bf16 v[66:81], v[214:217], v[110:113], v[66:81]
	v_cndmask_b32_e32 v154, v228, v227, vcc
	v_sqrt_f32_e64 v154, -v154
	v_lshlrev_b32_e32 v46, 16, v225
	v_mul_f32_e32 v46, v49, v46
	v_mul_f32_e32 v210, v154, v46
	v_mul_f32_e32 v158, v205, v204
	v_mfma_f32_32x32x16_bf16 v[50:65], v[214:217], v[106:109], v[50:65]
	s_nop 3
	v_add_f32_e32 v49, v190, v66
	v_mul_f32_e32 v49, 0xbfb8aa3b, v49
	v_exp_f32_e32 v49, v49
	v_mul_f32_e32 v158, v42, v158
	v_mul_f32_e32 v217, v40, v158
	v_mul_f32_e32 v158, v207, v206
	v_add_f32_e32 v49, 1.0, v49
	s_nop 0
	v_add_f32_e32 v46, v189, v50
	v_mul_f32_e32 v46, 0xbfb8aa3b, v46
	v_exp_f32_e32 v46, v46
	v_rcp_f32_e32 v49, v49
	s_waitcnt lgkmcnt(0)
; __device__ __forceinline__ float bf2f(bf16_t b) { return __uint_as_float(((unsigned)b) << 16); }
; __device__ __forceinline__ float fast_sigmoid(float x) { return __builtin_amdgcn_rcpf(1.0f + __builtin_amdgcn_exp2f(-1.4426950408889634f * x)); }
; template <int DIR>
; __device__ __forceinline__ void scan_dir(PP p, const bf16_t* xs, const ScanW& w, ScanW& wn, int ndir, int nct, bool do_next, int n, int ct, int l31, int hl, int id, int rowbase, bool latent, float (&hf)[2][16]) {
;     ...
;         for (int i = 0; i < 16; ++i) {
;             const int token = 32 * rt + 8 * (i >> 2) + 4 * hl + (i & 3);
;             const float xv = bf2f(xs[token * XS + ch]);
;             const float rr = fast_sigmoid(ga[i] + ba), ii = fast_sigmoid(gi[i] + bi);
;             const float la2 = rr * sp8l2;
;             const float av = __builtin_amdgcn_exp2f(la2);
;             const float t2 = la2 * 1.3862943611f;
;             float em1p = t2 * (1.0f + t2 * (0.5f + t2 * (0.16666667f + t2 * (0.041666668f + t2 * 0.0083333333f)))), em1e = __builtin_fmaf(av, av, -1.0f);
;             asm volatile("" : "+v"(em1p), "+v"(em1e));
;             const float em1 = (t2 > -0.1f) ? em1p : em1e;
;             a[rt][i] = av; u[rt][i] = __builtin_amdgcn_sqrtf(-em1) * (ii * xv);
;         }
	v_lshlrev_b32_e32 v50, 16, v124
	v_add_f32_e32 v52, v189, v52
	v_add_f32_e32 v46, 1.0, v46
	v_rcp_f32_e32 v46, v46
	v_mul_f32_e32 v49, v49, v50
	v_add_f32_e32 v50, v189, v51
	v_mul_f32_e32 v50, 0xbfb8aa3b, v50
	v_exp_f32_e32 v50, v50
	v_mul_f32_e32 v66, v193, v46
	v_exp_f32_e32 v46, v66
	v_mul_f32_e32 v66, 0x3fb17218, v66
	v_fmamk_f32 v154, v66, 0x3c088888, v186
	v_fmaak_f32 v154, v66, v154, 0x3e2aaaab
	v_add_f32_e32 v50, 1.0, v50
	v_fma_f32 v154, v66, v154, 0.5
	v_add_f32_e32 v51, v190, v67
	v_rcp_f32_e32 v50, v50
	v_fma_f32 v154, v66, v154, 1.0
	v_mul_f32_e32 v51, 0xbfb8aa3b, v51
	v_mul_f32_e32 v154, v66, v154
	v_fma_f32 v155, v46, v46, -1.0
	v_exp_f32_e32 v51, v51
	v_cmp_lt_f32_e32 vcc, s76, v66
	v_add_f32_e32 v51, 1.0, v51
	v_cndmask_b32_e32 v66, v155, v154, vcc
	v_mul_f32_e32 v154, v193, v50
	v_exp_f32_e32 v50, v154
	v_mul_f32_e32 v154, 0x3fb17218, v154
	v_sqrt_f32_e64 v66, -v66
	v_fmamk_f32 v155, v154, 0x3c088888, v186
	v_rcp_f32_e32 v51, v51
	v_fmaak_f32 v155, v154, v155, 0x3e2aaaab
	v_fma_f32 v155, v154, v155, 0.5
	v_fma_f32 v155, v154, v155, 1.0
	v_mul_f32_e32 v155, v154, v155
	v_fma_f32 v156, v50, v50, -1.0
	v_mul_f32_e32 v49, v49, v66
	s_waitcnt lgkmcnt(0)
	v_lshlrev_b32_e32 v66, 16, v125
	v_mul_f32_e32 v52, 0xbfb8aa3b, v52
	v_add_f32_e32 v67, v190, v68
	v_mul_f32_e32 v51, v51, v66
	v_exp_f32_e32 v52, v52
	v_mul_f32_e32 v67, 0xbfb8aa3b, v67
	v_exp_f32_e32 v67, v67
	v_cmp_lt_f32_e32 vcc, s76, v154
	v_add_f32_e32 v52, 1.0, v52
	v_rcp_f32_e32 v52, v52
	s_waitcnt lgkmcnt(0)
	v_lshlrev_b32_e32 v68, 16, v126
	v_add_f32_e32 v66, 1.0, v67
	v_add_f32_e32 v53, v189, v53
	v_cndmask_b32_e32 v154, v156, v155, vcc
	v_rcp_f32_e32 v67, v66
	v_mul_f32_e32 v53, 0xbfb8aa3b, v53
	v_sqrt_f32_e64 v154, -v154
	v_exp_f32_e32 v53, v53
	v_mul_f32_e32 v52, v193, v52
	v_exp_f32_e32 v66, v52
	v_mul_f32_e32 v52, 0x3fb17218, v52
	v_mul_f32_e32 v67, v67, v68
	v_add_f32_e32 v68, v190, v69
	v_mul_f32_e32 v51, v51, v154
	v_fmamk_f32 v154, v52, 0x3c088888, v186
	v_mul_f32_e32 v68, 0xbfb8aa3b, v68
	v_add_f32_e32 v53, 1.0, v53
	v_fmaak_f32 v154, v52, v154, 0x3e2aaaab
	v_exp_f32_e32 v68, v68
	v_rcp_f32_e32 v53, v53
	v_fma_f32 v154, v52, v154, 0.5
	v_fma_f32 v154, v52, v154, 1.0
	v_mul_f32_e32 v154, v52, v154
	v_fma_f32 v155, v66, v66, -1.0
	v_cmp_lt_f32_e32 vcc, s76, v52
	v_add_f32_e32 v68, 1.0, v68
	v_mul_f32_e32 v53, v193, v53
	v_cndmask_b32_e32 v52, v155, v154, vcc
	v_rcp_f32_e32 v154, v68
	v_exp_f32_e32 v68, v53
	v_mul_f32_e32 v53, 0x3fb17218, v53
	v_fmamk_f32 v155, v53, 0x3c088888, v186
	v_fmaak_f32 v155, v53, v155, 0x3e2aaaab
	v_fma_f32 v155, v53, v155, 0.5
	v_fma_f32 v155, v53, v155, 1.0
	v_sqrt_f32_e64 v52, -v52
	v_mul_f32_e32 v155, v53, v155
	v_fma_f32 v156, v68, v68, -1.0
	v_cmp_lt_f32_e32 vcc, s76, v53
	v_mul_f32_e32 v67, v67, v52
	s_waitcnt lgkmcnt(0)
	v_lshlrev_b32_e32 v52, 16, v127
	v_cndmask_b32_e32 v53, v156, v155, vcc
	v_sqrt_f32_e64 v53, -v53
	v_mul_f32_e32 v52, v154, v52
	v_add_f32_e32 v56, v189, v56
	v_mul_f32_e32 v56, 0xbfb8aa3b, v56
	v_mul_f32_e32 v69, v53, v52
	v_add_f32_e32 v53, v189, v54
	v_add_f32_e32 v54, v190, v70
	v_mul_f32_e32 v54, 0xbfb8aa3b, v54
	v_exp_f32_e32 v54, v54
	v_mul_f32_e32 v53, 0xbfb8aa3b, v53
	v_exp_f32_e32 v53, v53
	s_waitcnt lgkmcnt(0)
	v_lshlrev_b32_e32 v70, 16, v128
	v_add_f32_e32 v52, 1.0, v54
	v_rcp_f32_e32 v54, v52
	v_add_f32_e32 v53, 1.0, v53
	v_rcp_f32_e32 v53, v53
	v_exp_f32_e32 v56, v56
	v_mul_f32_e32 v70, v54, v70
	v_add_f32_e32 v54, v189, v55
	v_mul_f32_e32 v54, 0xbfb8aa3b, v54
	v_exp_f32_e32 v54, v54
	v_mul_f32_e32 v53, v193, v53
	v_exp_f32_e32 v52, v53
	v_mul_f32_e32 v53, 0x3fb17218, v53
	v_fmamk_f32 v154, v53, 0x3c088888, v186
	v_fmaak_f32 v154, v53, v154, 0x3e2aaaab
	v_add_f32_e32 v54, 1.0, v54
	v_fma_f32 v154, v53, v154, 0.5
	v_add_f32_e32 v55, v190, v71
	v_rcp_f32_e32 v54, v54
	v_fma_f32 v154, v53, v154, 1.0
	v_mul_f32_e32 v55, 0xbfb8aa3b, v55
	v_mul_f32_e32 v154, v53, v154
	v_fma_f32 v155, v52, v52, -1.0
	v_exp_f32_e32 v55, v55
	v_cmp_lt_f32_e32 vcc, s76, v53
	v_add_f32_e32 v55, 1.0, v55
	v_cndmask_b32_e32 v53, v155, v154, vcc
	v_mul_f32_e32 v154, v193, v54
	v_exp_f32_e32 v54, v154
	v_mul_f32_e32 v154, 0x3fb17218, v154
	v_sqrt_f32_e64 v53, -v53
	v_fmamk_f32 v155, v154, 0x3c088888, v186
	v_rcp_f32_e32 v55, v55
	v_fmaak_f32 v155, v154, v155, 0x3e2aaaab
	v_fma_f32 v155, v154, v155, 0.5
	v_fma_f32 v155, v154, v155, 1.0
	v_mul_f32_e32 v155, v154, v155
	v_fma_f32 v156, v54, v54, -1.0
	v_mul_f32_e32 v53, v53, v70
	s_waitcnt lgkmcnt(0)
	v_lshlrev_b32_e32 v70, 16, v129
	v_add_f32_e32 v71, v190, v72
	v_mul_f32_e32 v55, v55, v70
	v_mul_f32_e32 v71, 0xbfb8aa3b, v71
	v_exp_f32_e32 v71, v71
	v_add_f32_e32 v56, 1.0, v56
	v_cmp_lt_f32_e32 vcc, s76, v154
	v_rcp_f32_e32 v56, v56
	s_waitcnt lgkmcnt(0)
	v_lshlrev_b32_e32 v72, 16, v130
	v_add_f32_e32 v70, 1.0, v71
	v_add_f32_e32 v57, v189, v57
	v_cndmask_b32_e32 v154, v156, v155, vcc
	v_rcp_f32_e32 v71, v70
	v_mul_f32_e32 v57, 0xbfb8aa3b, v57
	v_sqrt_f32_e64 v154, -v154
	v_exp_f32_e32 v57, v57
	v_mul_f32_e32 v56, v193, v56
	v_exp_f32_e32 v70, v56
	v_mul_f32_e32 v56, 0x3fb17218, v56
	v_mul_f32_e32 v71, v71, v72
	v_add_f32_e32 v72, v190, v73
	v_mul_f32_e32 v55, v154, v55
	v_fmamk_f32 v154, v56, 0x3c088888, v186
	v_mul_f32_e32 v72, 0xbfb8aa3b, v72
	v_add_f32_e32 v57, 1.0, v57
	v_fmaak_f32 v154, v56, v154, 0x3e2aaaab
	v_exp_f32_e32 v72, v72
	v_rcp_f32_e32 v57, v57
	v_fma_f32 v154, v56, v154, 0.5
	v_fma_f32 v154, v56, v154, 1.0
	v_mul_f32_e32 v154, v56, v154
	v_fma_f32 v155, v70, v70, -1.0
	v_cmp_lt_f32_e32 vcc, s76, v56
	v_add_f32_e32 v72, 1.0, v72
	v_mul_f32_e32 v57, v193, v57
	v_cndmask_b32_e32 v56, v155, v154, vcc
	v_rcp_f32_e32 v154, v72
	v_exp_f32_e32 v72, v57
	v_mul_f32_e32 v57, 0x3fb17218, v57
	v_fmamk_f32 v155, v57, 0x3c088888, v186
	v_fmaak_f32 v155, v57, v155, 0x3e2aaaab
	v_fma_f32 v155, v57, v155, 0.5
	v_fma_f32 v155, v57, v155, 1.0
	v_sqrt_f32_e64 v56, -v56
	v_mul_f32_e32 v155, v57, v155
	v_fma_f32 v156, v72, v72, -1.0
	v_cmp_lt_f32_e32 vcc, s76, v57
	v_mul_f32_e32 v71, v56, v71
	s_waitcnt lgkmcnt(0)
; __device__ __forceinline__ float bf2f(bf16_t b) { return __uint_as_float(((unsigned)b) << 16); }
; __device__ __forceinline__ float fast_sigmoid(float x) { return __builtin_amdgcn_rcpf(1.0f + __builtin_amdgcn_exp2f(-1.4426950408889634f * x)); }
; template <int DIR>
; __device__ __forceinline__ void scan_dir(PP p, const bf16_t* xs, const ScanW& w, ScanW& wn, int ndir, int nct, bool do_next, int n, int ct, int l31, int hl, int id, int rowbase, bool latent, float (&hf)[2][16]) {
;     ...
;         for (int i = 0; i < 16; ++i) {
;             const int token = 32 * rt + 8 * (i >> 2) + 4 * hl + (i & 3);
;             const float xv = bf2f(xs[token * XS + ch]);
;             const float rr = fast_sigmoid(ga[i] + ba), ii = fast_sigmoid(gi[i] + bi);
;             const float la2 = rr * sp8l2;
;             const float av = __builtin_amdgcn_exp2f(la2);
;             const float t2 = la2 * 1.3862943611f;
;             float em1p = t2 * (1.0f + t2 * (0.5f + t2 * (0.16666667f + t2 * (0.041666668f + t2 * 0.0083333333f)))), em1e = __builtin_fmaf(av, av, -1.0f);
;             asm volatile("" : "+v"(em1p), "+v"(em1e));
;             const float em1 = (t2 > -0.1f) ? em1p : em1e;
;             a[rt][i] = av; u[rt][i] = __builtin_amdgcn_sqrtf(-em1) * (ii * xv);
;         }
	v_lshlrev_b32_e32 v56, 16, v131
	v_cndmask_b32_e32 v57, v156, v155, vcc
	v_sqrt_f32_e64 v57, -v57
	v_mul_f32_e32 v56, v154, v56
	v_add_f32_e32 v60, v189, v60
	v_mul_f32_e32 v60, 0xbfb8aa3b, v60
	v_mul_f32_e32 v73, v57, v56
	v_add_f32_e32 v57, v189, v58
	v_add_f32_e32 v58, v190, v74
	v_mul_f32_e32 v58, 0xbfb8aa3b, v58
	v_exp_f32_e32 v58, v58
	v_mul_f32_e32 v57, 0xbfb8aa3b, v57
	v_exp_f32_e32 v57, v57
	s_waitcnt lgkmcnt(0)
	v_lshlrev_b32_e32 v74, 16, v132
	v_add_f32_e32 v56, 1.0, v58
	v_rcp_f32_e32 v58, v56
	v_add_f32_e32 v57, 1.0, v57
	v_rcp_f32_e32 v57, v57
	v_exp_f32_e32 v60, v60
	v_mul_f32_e32 v74, v58, v74
	v_add_f32_e32 v58, v189, v59
	v_mul_f32_e32 v58, 0xbfb8aa3b, v58
	v_exp_f32_e32 v58, v58
	v_mul_f32_e32 v57, v193, v57
	v_exp_f32_e32 v56, v57
	v_mul_f32_e32 v57, 0x3fb17218, v57
	v_fmamk_f32 v154, v57, 0x3c088888, v186
	v_fmaak_f32 v154, v57, v154, 0x3e2aaaab
	v_add_f32_e32 v58, 1.0, v58
	v_fma_f32 v154, v57, v154, 0.5
	v_add_f32_e32 v59, v190, v75
	v_rcp_f32_e32 v58, v58
	v_fma_f32 v154, v57, v154, 1.0
	v_mul_f32_e32 v59, 0xbfb8aa3b, v59
	v_mul_f32_e32 v154, v57, v154
	v_fma_f32 v155, v56, v56, -1.0
	v_exp_f32_e32 v59, v59
	v_cmp_lt_f32_e32 vcc, s76, v57
	v_add_f32_e32 v59, 1.0, v59
	v_cndmask_b32_e32 v57, v155, v154, vcc
	v_mul_f32_e32 v154, v193, v58
	v_exp_f32_e32 v58, v154
	v_mul_f32_e32 v154, 0x3fb17218, v154
	v_sqrt_f32_e64 v57, -v57
	v_fmamk_f32 v155, v154, 0x3c088888, v186
	v_rcp_f32_e32 v59, v59
	v_fmaak_f32 v155, v154, v155, 0x3e2aaaab
	v_fma_f32 v155, v154, v155, 0.5
	v_fma_f32 v155, v154, v155, 1.0
	v_mul_f32_e32 v155, v154, v155
	v_fma_f32 v156, v58, v58, -1.0
	v_mul_f32_e32 v57, v57, v74
	s_waitcnt lgkmcnt(0)
	v_lshlrev_b32_e32 v74, 16, v133
	v_add_f32_e32 v75, v190, v76
	v_mul_f32_e32 v59, v59, v74
	v_mul_f32_e32 v75, 0xbfb8aa3b, v75
	v_exp_f32_e32 v75, v75
	v_add_f32_e32 v60, 1.0, v60
	v_cmp_lt_f32_e32 vcc, s76, v154
	v_rcp_f32_e32 v60, v60
	s_waitcnt lgkmcnt(0)
	v_lshlrev_b32_e32 v76, 16, v134
	v_add_f32_e32 v74, 1.0, v75
	v_add_f32_e32 v61, v189, v61
	v_cndmask_b32_e32 v154, v156, v155, vcc
	v_rcp_f32_e32 v75, v74
	v_mul_f32_e32 v61, 0xbfb8aa3b, v61
	v_sqrt_f32_e64 v154, -v154
	v_exp_f32_e32 v61, v61
	v_mul_f32_e32 v60, v193, v60
	v_exp_f32_e32 v74, v60
	v_mul_f32_e32 v60, 0x3fb17218, v60
	v_mul_f32_e32 v75, v75, v76
	v_add_f32_e32 v76, v190, v77
	v_mul_f32_e32 v59, v154, v59
	v_fmamk_f32 v154, v60, 0x3c088888, v186
	v_mul_f32_e32 v76, 0xbfb8aa3b, v76
	v_add_f32_e32 v61, 1.0, v61
	v_fmaak_f32 v154, v60, v154, 0x3e2aaaab
	v_exp_f32_e32 v76, v76
	v_rcp_f32_e32 v61, v61
	v_fma_f32 v154, v60, v154, 0.5
	v_fma_f32 v154, v60, v154, 1.0
	v_mul_f32_e32 v154, v60, v154
	v_fma_f32 v155, v74, v74, -1.0
	v_cmp_lt_f32_e32 vcc, s76, v60
	v_add_f32_e32 v76, 1.0, v76
	v_mul_f32_e32 v61, v193, v61
	v_cndmask_b32_e32 v60, v155, v154, vcc
	v_rcp_f32_e32 v154, v76
	v_exp_f32_e32 v76, v61
	v_mul_f32_e32 v61, 0x3fb17218, v61
	v_fmamk_f32 v155, v61, 0x3c088888, v186
	v_fmaak_f32 v155, v61, v155, 0x3e2aaaab
	v_fma_f32 v155, v61, v155, 0.5
	v_fma_f32 v155, v61, v155, 1.0
	v_sqrt_f32_e64 v60, -v60
	v_mul_f32_e32 v155, v61, v155
	v_fma_f32 v156, v76, v76, -1.0
	v_cmp_lt_f32_e32 vcc, s76, v61
	v_mul_f32_e32 v75, v60, v75
	s_waitcnt lgkmcnt(0)
	v_lshlrev_b32_e32 v60, 16, v135
	v_cndmask_b32_e32 v61, v156, v155, vcc
	v_sqrt_f32_e64 v61, -v61
	v_mul_f32_e32 v60, v154, v60
	v_add_f32_e32 v64, v189, v64
	v_mul_f32_e32 v64, 0xbfb8aa3b, v64
	v_mul_f32_e32 v77, v61, v60
	v_add_f32_e32 v61, v189, v62
	v_add_f32_e32 v62, v190, v78
	v_mul_f32_e32 v62, 0xbfb8aa3b, v62
	v_mul_f32_e32 v61, 0xbfb8aa3b, v61
	v_exp_f32_e32 v62, v62
	v_exp_f32_e32 v61, v61
	s_waitcnt lgkmcnt(0)
	v_lshlrev_b32_e32 v78, 16, v136
	v_exp_f32_e32 v64, v64
	v_add_f32_e32 v60, 1.0, v62
	v_add_f32_e32 v61, 1.0, v61
	v_rcp_f32_e32 v62, v60
	v_rcp_f32_e32 v61, v61
	v_add_f32_e32 v65, v189, v65
	v_mul_f32_e32 v65, 0xbfb8aa3b, v65
	v_mul_f32_e32 v78, v62, v78
	v_add_f32_e32 v62, v189, v63
	v_mul_f32_e32 v61, v193, v61
	v_mul_f32_e32 v62, 0xbfb8aa3b, v62
	v_exp_f32_e32 v60, v61
	v_mul_f32_e32 v61, 0x3fb17218, v61
	v_exp_f32_e32 v62, v62
	v_fmamk_f32 v154, v61, 0x3c088888, v186
	v_fmaak_f32 v154, v61, v154, 0x3e2aaaab
	v_fma_f32 v154, v61, v154, 0.5
	v_fma_f32 v154, v61, v154, 1.0
	v_add_f32_e32 v62, 1.0, v62
	v_mul_f32_e32 v154, v61, v154
	v_fma_f32 v155, v60, v60, -1.0
	v_cmp_lt_f32_e32 vcc, s76, v61
	v_add_f32_e32 v63, v190, v79
	v_rcp_f32_e32 v62, v62
	v_mul_f32_e32 v63, 0xbfb8aa3b, v63
	v_cndmask_b32_e32 v61, v155, v154, vcc
	v_sqrt_f32_e64 v61, -v61
	v_exp_f32_e32 v63, v63
	v_mul_f32_e32 v154, v193, v62
	v_exp_f32_e32 v62, v154
	v_mul_f32_e32 v154, 0x3fb17218, v154
	v_add_f32_e32 v63, 1.0, v63
	v_fmamk_f32 v155, v154, 0x3c088888, v186
	v_mul_f32_e32 v61, v61, v78
	s_waitcnt lgkmcnt(0)
; __device__ __forceinline__ float bf2f(bf16_t b) { return __uint_as_float(((unsigned)b) << 16); }
; __device__ __forceinline__ void scan_loadw(PP p, int dir, int n, int ct, int l31, int hl, ScanW& w) {
;     unsigned chv = (unsigned)(32 * ct + l31); asm volatile("" : "+v"(chv));
;     const unsigned ch = (unsigned)(dir * 512 + 64 * n) + chv;
;     w.ba = p->lru_b_a[ch]; w.bi = p->lru_b_i[ch];
;     w.sp8l2 = ((const float*)(p->ws + WS_SP8))[ch] * 1.4426950408889634f;
;     const bf16_t* wa_b = (const bf16_t*)(p->ws + WS_LRU) + (size_t)((dir * 2 + 0) * 8 + n) * 4096;
;     const bf16_t* wi_b = (const bf16_t*)(p->ws + WS_LRU) + (size_t)((dir * 2 + 1) * 8 + n) * 4096;
;     const unsigned lo = chv * 64u + 8u * (unsigned)hl;
; #pragma unroll
;     for (int st = 0; st < 4; ++st) { w.wfa[st] = *(const bf16x8*)(wa_b + lo + 16 * st); w.wfi[st] = *(const bf16x8*)(wi_b + lo + 16 * st); }
; template <int DIR>
; __device__ __forceinline__ void scan_dir(PP p, const bf16_t* xs, const ScanW& w, ScanW& wn, int ndir, int nct, bool do_next, int n, int ct, int l31, int hl, int id, int rowbase, bool latent, float (&hf)[2][16]) {
;     ...
;         for (int i = 0; i < 16; ++i) {
;             const int token = 32 * rt + 8 * (i >> 2) + 4 * hl + (i & 3);
;             const float xv = bf2f(xs[token * XS + ch]);
;             const float rr = fast_sigmoid(ga[i] + ba), ii = fast_sigmoid(gi[i] + bi);
;             const float la2 = rr * sp8l2;
;             const float av = __builtin_amdgcn_exp2f(la2);
;             const float t2 = la2 * 1.3862943611f;
;             float em1p = t2 * (1.0f + t2 * (0.5f + t2 * (0.16666667f + t2 * (0.041666668f + t2 * 0.0083333333f)))), em1e = __builtin_fmaf(av, av, -1.0f);
;             asm volatile("" : "+v"(em1p), "+v"(em1e));
;             const float em1 = (t2 > -0.1f) ? em1p : em1e;
;             a[rt][i] = av; u[rt][i] = __builtin_amdgcn_sqrtf(-em1) * (ii * xv);
;         }
;     }
;     float Ao[8], Ho[8], Ap[8], Hp[8];
; #pragma unroll
;     for (int k = 0; k < 8; ++k) {
;         const int rt = k >> 2, g = k & 3;
;         float H = 0.f, A = 1.f;
; #pragma unroll
;         for (int jj = 0; jj < 4; ++jj) { const int j = DIR ? 3 - jj : jj; const float av = a[rt][4 * g + j]; H = av * H + u[rt][4 * g + j]; A *= av; }
;         Ao[k] = A; Ho[k] = H; Ap[k] = __shfl_xor(A, 32); Hp[k] = __shfl_xor(H, 32);
;     }
	v_lshlrev_b32_e32 v78, 16, v137
	v_add_f32_e32 v79, v190, v80
	v_rcp_f32_e32 v63, v63
	v_fmaak_f32 v155, v154, v155, 0x3e2aaaab
	v_mul_f32_e32 v79, 0xbfb8aa3b, v79
	v_fma_f32 v155, v154, v155, 0.5
	v_exp_f32_e32 v79, v79
	v_exp_f32_e32 v65, v65
	v_fma_f32 v155, v154, v155, 1.0
	v_mul_f32_e32 v155, v154, v155
	v_fma_f32 v156, v62, v62, -1.0
	v_add_f32_e32 v64, 1.0, v64
	v_cmp_lt_f32_e32 vcc, s76, v154
	v_mul_f32_e32 v63, v63, v78
	v_rcp_f32_e32 v64, v64
	v_cndmask_b32_e32 v154, v156, v155, vcc
	v_add_f32_e32 v79, 1.0, v79
	v_add_f32_e32 v65, 1.0, v65
	v_sqrt_f32_e64 v154, -v154
	v_rcp_f32_e32 v79, v79
	v_rcp_f32_e32 v65, v65
	v_mul_f32_e32 v80, v193, v64
	s_waitcnt lgkmcnt(0)
	v_lshlrev_b32_e32 v78, 16, v138
	v_exp_f32_e32 v64, v80
	v_mul_f32_e32 v80, 0x3fb17218, v80
	v_fma_f32 v156, 0, v205, v211
	v_mul_f32_e32 v63, v154, v63
	v_fmamk_f32 v154, v80, 0x3c088888, v186
	v_mul_f32_e32 v78, v79, v78
	v_add_f32_e32 v79, v190, v81
	v_mul_f32_e32 v65, v193, v65
	v_fma_f32 v156, v204, v156, v208
	v_fmaak_f32 v154, v80, v154, 0x3e2aaaab
	v_mul_f32_e32 v79, 0xbfb8aa3b, v79
	v_exp_f32_e32 v213, v65
	v_mul_f32_e32 v65, 0x3fb17218, v65
	v_fma_f32 v156, v42, v156, v43
	v_fma_f32 v154, v80, v154, 0.5
	v_exp_f32_e32 v79, v79
	v_fmamk_f32 v81, v65, 0x3c088888, v186
	v_fma_f32 v216, v40, v156, v41
	v_fma_f32 v156, 0, v207, v210
	v_fma_f32 v154, v80, v154, 1.0
	v_fmaak_f32 v81, v65, v81, 0x3e2aaaab
	v_fma_f32 v156, v206, v156, v209
	v_mul_f32_e32 v154, v80, v154
	v_fma_f32 v155, v64, v64, -1.0
	v_fma_f32 v81, v65, v81, 0.5
	v_fma_f32 v156, v45, v156, v48
	v_cmp_lt_f32_e32 vcc, s76, v80
	ds_read_u16 v0, v0 offset:61360
	v_fma_f32 v81, v65, v81, 1.0
	v_fma_f32 v221, v44, v156, v47
	v_fma_f32 v156, 0, v68, v69
	v_cndmask_b32_e32 v80, v155, v154, vcc
	v_add_f32_e32 v79, 1.0, v79
	v_mul_f32_e32 v81, v65, v81
	v_fma_f32 v154, v213, v213, -1.0
	v_cmp_lt_f32_e32 vcc, s76, v65
	v_fma_f32 v156, v66, v156, v67
	v_rcp_f32_e32 v79, v79
	v_fma_f32 v156, v50, v156, v51
	v_cndmask_b32_e32 v65, v154, v81, vcc
	v_sqrt_f32_e64 v65, -v65
	v_mul_f32_e32 v158, v45, v158
	v_fma_f32 v225, v46, v156, v49
	v_fma_f32 v156, 0, v72, v73
	v_mul_f32_e32 v222, v44, v158
	v_mul_f32_e32 v158, v68, v66
	v_fma_f32 v156, v70, v156, v71
	v_sqrt_f32_e64 v80, -v80
	s_waitcnt lgkmcnt(0)
	v_lshlrev_b32_e32 v0, 16, v0
	v_mul_f32_e32 v158, v50, v158
	v_fma_f32 v156, v54, v156, v55
	v_mul_f32_e32 v0, v79, v0
	v_mul_f32_e32 v226, v46, v158
	v_mul_f32_e32 v158, v72, v70
	v_fma_f32 v229, v52, v156, v53
	v_fma_f32 v156, 0, v76, v77
	v_mul_f32_e32 v214, v65, v0
	v_and_b32_e32 v65, 64, v188
	v_mul_f32_e32 v158, v54, v158
	v_fma_f32 v156, v74, v156, v75
	v_xor_b32_e32 v0, 32, v188
	v_add_u32_e32 v65, 64, v65
	v_mul_f32_e32 v230, v52, v158
	v_mul_f32_e32 v158, v76, v74
	v_fma_f32 v156, v58, v156, v59
	v_mul_f32_e32 v81, v80, v78
	v_cmp_lt_i32_e32 vcc, v0, v65
	v_fma_f32 v65, 0, v198, v199
	v_fma_f32 v154, 0, v202, v203
	v_mul_f32_e32 v158, v58, v158
	v_fma_f32 v233, v56, v156, v57
	v_fma_f32 v156, 0, v213, v214
	v_fma_f32 v65, v196, v65, v197
	v_mul_f32_e32 v78, v198, v196
	v_fma_f32 v154, v200, v154, v201
	v_mul_f32_e32 v155, v202, v200
	v_mul_f32_e32 v234, v56, v158
	v_fma_f32 v156, v64, v156, v81
	v_mul_f32_e32 v158, v213, v64
	v_cndmask_b32_e32 v0, v188, v0, vcc
	v_fma_f32 v65, v147, v65, v195
	v_mul_f32_e32 v78, v147, v78
	v_fma_f32 v154, v38, v154, v39
	v_mul_f32_e32 v155, v38, v155
	v_fma_f32 v156, v62, v156, v63
	v_mul_f32_e32 v159, v62, v158
	v_lshlrev_b32_e32 v0, 2, v0
	v_fma_f32 v65, v34, v65, v35
	v_mul_f32_e32 v78, v34, v78
	v_fma_f32 v154, v36, v154, v37
	v_mul_f32_e32 v155, v36, v155
	v_fma_f32 v158, v60, v156, v61
	v_mul_f32_e32 v156, v60, v159
	ds_bpermute_b32 v79, v0, v78
	ds_bpermute_b32 v80, v0, v65
	ds_bpermute_b32 v212, v0, v155
	ds_bpermute_b32 v215, v0, v154
	ds_bpermute_b32 v218, v0, v217
	ds_bpermute_b32 v219, v0, v216
	ds_bpermute_b32 v223, v0, v222
	ds_bpermute_b32 v224, v0, v221
	ds_bpermute_b32 v227, v0, v226
	ds_bpermute_b32 v228, v0, v225
	ds_bpermute_b32 v231, v0, v230
	ds_bpermute_b32 v232, v0, v229
	ds_bpermute_b32 v235, v0, v234
	ds_bpermute_b32 v236, v0, v233
	ds_bpermute_b32 v220, v0, v156
	ds_bpermute_b32 v237, v0, v158
	s_andn2_b64 vcc, exec, s[4:5]
	s_cbranch_vccnz .LBB0_447
	v_or_b32_e32 v118, 32, v148
	s_load_dwordx2 s[4:5], s[8:9], 0x58
	s_load_dwordx2 s[44:45], s[8:9], 0x68
	v_add_u32_e32 v0, s33, v118
	v_lshlrev_b64 v[114:115], 2, v[0:1]
	v_lshl_or_b32 v0, v118, 6, v149
	s_waitcnt lgkmcnt(0)
	v_lshl_add_u64 v[116:117], s[4:5], 0, v[114:115]
	global_load_dword v192, v[116:117], off
	v_lshl_add_u64 v[116:117], s[44:45], 0, v[114:115]
	global_load_dword v191, v[116:117], off
	v_lshlrev_b64 v[116:117], 1, v[0:1]
	v_lshl_add_u64 v[114:115], s[12:13], 0, v[114:115]
	v_lshl_add_u64 v[138:139], s[14:15], 0, v[116:117]
	v_lshl_add_u64 v[142:143], s[18:19], 0, v[116:117]
	global_load_dword v0, v[114:115], off
	s_nop 0
	global_load_dwordx4 v[114:117], v[138:139], off
	global_load_dwordx4 v[118:121], v[138:139], off offset:32
	global_load_dwordx4 v[122:125], v[138:139], off offset:64
	global_load_dwordx4 v[126:129], v[142:143], off offset:32
	global_load_dwordx4 v[130:133], v[142:143], off offset:64
	global_load_dwordx4 v[134:137], v[142:143], off
	s_nop 0
	global_load_dwordx4 v[138:141], v[138:139], off offset:96
	s_nop 0
	global_load_dwordx4 v[142:145], v[142:143], off offset:96
	s_waitcnt vmcnt(8)
	v_mul_f32_e32 v194, 0x3fb8aa3b, v0
